# attn fast path for full tiles + z hoist + sink via SMEM; rglru tile loops: packed f32 ops split into scalar ops
# speedup vs baseline: 1.0132x; 1.0056x over previous
.LBB0_1125:
	s_cmp_eq_u32 s39, 0
	s_cbranch_scc1 .Lattn_generic
	s_cmp_eq_u32 s39, 2
	s_cbranch_scc0 .Lattn_fast

.Lattn_fast:
	v_add_u32_e32 v241, s4, v159
	v_add_u32_e32 v201, v241, v161
	ds_read_b128 v[220:223], v201
	ds_read_b128 v[224:227], v201 offset:64
	ds_read_b128 v[228:231], v201 offset:2304
	ds_read_b128 v[232:235], v201 offset:2368
	ds_read_b128 v[236:239], v201 offset:4608
	ds_read_b128 v[252:255], v201 offset:4672
	s_waitcnt lgkmcnt(4)
	v_mfma_f32_16x16x32_bf16 v[40:43], v[220:223], v[16:19], 0
	v_mfma_f32_16x16x32_bf16 v[40:43], v[224:227], v[20:23], v[40:43]
	ds_read_b128 v[220:223], v201 offset:6912
	ds_read_b128 v[224:227], v201 offset:6976
	s_waitcnt lgkmcnt(4)
	v_mfma_f32_16x16x32_bf16 v[44:47], v[228:231], v[16:19], 0
	v_mfma_f32_16x16x32_bf16 v[44:47], v[232:235], v[20:23], v[44:47]
	ds_read_b128 v[228:231], v201 offset:9216
	ds_read_b128 v[232:235], v201 offset:9280
	s_waitcnt lgkmcnt(4)
	v_mfma_f32_16x16x32_bf16 v[48:51], v[236:239], v[16:19], 0
	v_mfma_f32_16x16x32_bf16 v[48:51], v[252:255], v[20:23], v[48:51]
	ds_read_b128 v[236:239], v201 offset:11520
	ds_read_b128 v[252:255], v201 offset:11584
	s_waitcnt lgkmcnt(4)
	v_mfma_f32_16x16x32_bf16 v[52:55], v[220:223], v[16:19], 0
	v_mfma_f32_16x16x32_bf16 v[52:55], v[224:227], v[20:23], v[52:55]
	ds_read_b128 v[220:223], v201 offset:13824
	ds_read_b128 v[224:227], v201 offset:13888
	s_waitcnt lgkmcnt(4)
	v_mfma_f32_16x16x32_bf16 v[56:59], v[228:231], v[16:19], 0
	v_mfma_f32_16x16x32_bf16 v[56:59], v[232:235], v[20:23], v[56:59]
	ds_read_b128 v[228:231], v201 offset:16128
	ds_read_b128 v[232:235], v201 offset:16192
	s_waitcnt lgkmcnt(4)
	v_mfma_f32_16x16x32_bf16 v[60:63], v[236:239], v[16:19], 0
	v_mfma_f32_16x16x32_bf16 v[60:63], v[252:255], v[20:23], v[60:63]
	s_waitcnt lgkmcnt(2)
	v_mfma_f32_16x16x32_bf16 v[64:67], v[220:223], v[16:19], 0
	v_mfma_f32_16x16x32_bf16 v[64:67], v[224:227], v[20:23], v[64:67]
	s_waitcnt lgkmcnt(0)
	v_mfma_f32_16x16x32_bf16 v[68:71], v[228:231], v[16:19], 0
	v_mfma_f32_16x16x32_bf16 v[68:71], v[232:235], v[20:23], v[68:71]
	s_nop 7
	v_max3_f32 v200, v40, v41, s68
	v_max3_f32 v202, v42, v43, s68
	v_max3_f32 v200, v200, v44, v45
	v_max3_f32 v202, v202, v46, v47
	v_max3_f32 v200, v200, v48, v49
	v_max3_f32 v202, v202, v50, v51
	v_max3_f32 v200, v200, v52, v53
	v_max3_f32 v202, v202, v54, v55
	v_max3_f32 v200, v200, v56, v57
	v_max3_f32 v202, v202, v58, v59
	v_max3_f32 v200, v200, v60, v61
	v_max3_f32 v202, v202, v62, v63
	v_max3_f32 v200, v200, v64, v65
	v_max3_f32 v202, v202, v66, v67
	v_max3_f32 v200, v200, v68, v69
	v_max3_f32 v202, v202, v70, v71
	v_max_f32_e32 v200, v200, v202
	ds_bpermute_b32 v72, v195, v200
	v_max_f32_e32 v151, v200, v200
	s_waitcnt lgkmcnt(0)
	v_max_f32_e32 v72, v72, v72
	v_max_f32_e32 v72, v151, v72
	ds_bpermute_b32 v151, v196, v72
	s_waitcnt lgkmcnt(0)
	v_max3_f32 v151, v153, v72, v151
	v_sub_f32_e32 v72, v153, v151
	v_exp_f32_e32 v72, v72
	v_sub_f32_e32 v40, v40, v151
	v_sub_f32_e32 v41, v41, v151
	v_sub_f32_e32 v42, v42, v151
	v_sub_f32_e32 v43, v43, v151
	v_sub_f32_e32 v44, v44, v151
	v_sub_f32_e32 v45, v45, v151
	v_sub_f32_e32 v46, v46, v151
	v_sub_f32_e32 v47, v47, v151
	v_sub_f32_e32 v48, v48, v151
	v_sub_f32_e32 v49, v49, v151
	v_sub_f32_e32 v50, v50, v151
	v_sub_f32_e32 v51, v51, v151
	v_sub_f32_e32 v52, v52, v151
	v_sub_f32_e32 v53, v53, v151
	v_sub_f32_e32 v54, v54, v151
	v_sub_f32_e32 v55, v55, v151
	v_sub_f32_e32 v56, v56, v151
	v_sub_f32_e32 v57, v57, v151
	v_sub_f32_e32 v58, v58, v151
	v_sub_f32_e32 v59, v59, v151
	v_sub_f32_e32 v60, v60, v151
	v_sub_f32_e32 v61, v61, v151
	v_sub_f32_e32 v62, v62, v151
	v_sub_f32_e32 v63, v63, v151
	v_sub_f32_e32 v64, v64, v151
	v_sub_f32_e32 v65, v65, v151
	v_sub_f32_e32 v66, v66, v151
	v_sub_f32_e32 v67, v67, v151
	v_sub_f32_e32 v68, v68, v151
	v_sub_f32_e32 v69, v69, v151
	v_sub_f32_e32 v70, v70, v151
	v_sub_f32_e32 v71, v71, v151
	v_mul_f32_e32 v149, v149, v72
	v_exp_f32_e32 v40, v40
	v_exp_f32_e32 v41, v41
	v_exp_f32_e32 v42, v42
	v_exp_f32_e32 v43, v43
	v_exp_f32_e32 v44, v44
	v_exp_f32_e32 v45, v45
	v_exp_f32_e32 v46, v46
	v_exp_f32_e32 v47, v47
	v_exp_f32_e32 v48, v48
	v_exp_f32_e32 v49, v49
	v_exp_f32_e32 v50, v50
	v_exp_f32_e32 v51, v51
	v_exp_f32_e32 v52, v52
	v_exp_f32_e32 v53, v53
	v_exp_f32_e32 v54, v54
	v_exp_f32_e32 v55, v55
	v_exp_f32_e32 v56, v56
	v_exp_f32_e32 v57, v57
	v_exp_f32_e32 v58, v58
	v_exp_f32_e32 v59, v59
	v_exp_f32_e32 v60, v60
	v_exp_f32_e32 v61, v61
	v_exp_f32_e32 v62, v62
	v_exp_f32_e32 v63, v63
	v_exp_f32_e32 v64, v64
	v_exp_f32_e32 v65, v65
	v_exp_f32_e32 v66, v66
	v_exp_f32_e32 v67, v67
	v_exp_f32_e32 v68, v68
	v_exp_f32_e32 v69, v69
	v_exp_f32_e32 v70, v70
	v_exp_f32_e32 v71, v71
	v_pk_mul_f32 v[38:39], v[38:39], v[72:73] op_sel_hi:[1,0]
	v_pk_mul_f32 v[36:37], v[36:37], v[72:73] op_sel_hi:[1,0]
	v_pk_mul_f32 v[34:35], v[34:35], v[72:73] op_sel_hi:[1,0]
	v_pk_mul_f32 v[32:33], v[32:33], v[72:73] op_sel_hi:[1,0]
	v_pk_mul_f32 v[30:31], v[30:31], v[72:73] op_sel_hi:[1,0]
	v_pk_mul_f32 v[28:29], v[28:29], v[72:73] op_sel_hi:[1,0]
	v_pk_mul_f32 v[26:27], v[26:27], v[72:73] op_sel_hi:[1,0]
	v_pk_mul_f32 v[24:25], v[24:25], v[72:73] op_sel_hi:[1,0]
	v_lshl_add_u32 v241, v160, 1, s38
	v_add_u32_e32 v241, v241, v162
	ds_read_b64_tr_b16 v[220:221], v241
	ds_read_b64_tr_b16 v[222:223], v241 offset:2304
	ds_read_b64_tr_b16 v[224:225], v241 offset:32
	ds_read_b64_tr_b16 v[226:227], v241 offset:2336
	ds_read_b64_tr_b16 v[228:229], v241 offset:64
	ds_read_b64_tr_b16 v[230:231], v241 offset:2368
	ds_read_b64_tr_b16 v[232:233], v241 offset:96
	ds_read_b64_tr_b16 v[234:235], v241 offset:2400
	ds_read_b64_tr_b16 v[236:237], v241 offset:4608
	ds_read_b64_tr_b16 v[238:239], v241 offset:6912
	ds_read_b64_tr_b16 v[252:253], v241 offset:4640
	ds_read_b64_tr_b16 v[254:255], v241 offset:6944
	v_add_f32_e32 v149, v40, v149
	v_add_f32_e32 v149, v41, v149
	v_add_f32_e32 v149, v42, v149
	v_add_f32_e32 v149, v43, v149
	v_add_f32_e32 v149, v44, v149
	v_add_f32_e32 v149, v45, v149
	v_add_f32_e32 v149, v46, v149
	v_add_f32_e32 v149, v47, v149
	v_add_f32_e32 v149, v48, v149
	v_add_f32_e32 v149, v49, v149
	v_add_f32_e32 v149, v50, v149
	v_add_f32_e32 v149, v51, v149
	v_add_f32_e32 v149, v52, v149
	v_add_f32_e32 v149, v53, v149
	v_add_f32_e32 v149, v54, v149
	v_add_f32_e32 v149, v55, v149
	v_add_f32_e32 v149, v56, v149
	v_add_f32_e32 v149, v57, v149
	v_add_f32_e32 v149, v58, v149
	v_add_f32_e32 v149, v59, v149
	v_add_f32_e32 v149, v60, v149
	v_add_f32_e32 v149, v61, v149
	v_add_f32_e32 v149, v62, v149
	v_add_f32_e32 v149, v63, v149
	v_add_f32_e32 v149, v64, v149
	v_add_f32_e32 v149, v65, v149
	v_add_f32_e32 v149, v66, v149
	v_add_f32_e32 v149, v67, v149
	v_add_f32_e32 v149, v68, v149
	v_add_f32_e32 v149, v69, v149
	v_add_f32_e32 v149, v70, v149
	v_add_f32_e32 v149, v71, v149
	v_cvt_pk_bf16_f32 v40, v40, v41
	v_cvt_pk_bf16_f32 v41, v42, v43
	v_cvt_pk_bf16_f32 v42, v44, v45
	v_cvt_pk_bf16_f32 v43, v46, v47
	v_cvt_pk_bf16_f32 v48, v48, v49
	v_cvt_pk_bf16_f32 v49, v50, v51
	v_cvt_pk_bf16_f32 v50, v52, v53
	v_cvt_pk_bf16_f32 v51, v54, v55
	v_cvt_pk_bf16_f32 v56, v56, v57
	v_cvt_pk_bf16_f32 v57, v58, v59
	v_cvt_pk_bf16_f32 v58, v60, v61
	v_cvt_pk_bf16_f32 v59, v62, v63
	v_cvt_pk_bf16_f32 v64, v64, v65
	v_cvt_pk_bf16_f32 v65, v66, v67
	v_cvt_pk_bf16_f32 v66, v68, v69
	v_cvt_pk_bf16_f32 v67, v70, v71
	s_nop 1
	s_waitcnt lgkmcnt(10)
	v_mfma_f32_16x16x32_bf16 v[36:39], v[220:223], v[40:43], v[36:39]
	ds_read_b64_tr_b16 v[220:221], v241 offset:4672
	ds_read_b64_tr_b16 v[222:223], v241 offset:6976
	s_waitcnt lgkmcnt(10)
	v_mfma_f32_16x16x32_bf16 v[32:35], v[224:227], v[40:43], v[32:35]
	ds_read_b64_tr_b16 v[224:225], v241 offset:4704
	ds_read_b64_tr_b16 v[226:227], v241 offset:7008
	s_waitcnt lgkmcnt(10)
	v_mfma_f32_16x16x32_bf16 v[28:31], v[228:231], v[40:43], v[28:31]
	ds_read_b64_tr_b16 v[228:229], v241 offset:9216
	ds_read_b64_tr_b16 v[230:231], v241 offset:11520
	s_waitcnt lgkmcnt(10)
	v_mfma_f32_16x16x32_bf16 v[24:27], v[232:235], v[40:43], v[24:27]
	ds_read_b64_tr_b16 v[232:233], v241 offset:9248
	ds_read_b64_tr_b16 v[234:235], v241 offset:11552
	s_waitcnt lgkmcnt(10)
	v_mfma_f32_16x16x32_bf16 v[36:39], v[236:239], v[48:51], v[36:39]
	ds_read_b64_tr_b16 v[236:237], v241 offset:9280
	ds_read_b64_tr_b16 v[238:239], v241 offset:11584
	s_waitcnt lgkmcnt(10)
	v_mfma_f32_16x16x32_bf16 v[32:35], v[252:255], v[48:51], v[32:35]
	ds_read_b64_tr_b16 v[252:253], v241 offset:9312
	ds_read_b64_tr_b16 v[254:255], v241 offset:11616
	s_waitcnt lgkmcnt(10)
	v_mfma_f32_16x16x32_bf16 v[28:31], v[220:223], v[48:51], v[28:31]
	ds_read_b64_tr_b16 v[220:221], v241 offset:13824
	ds_read_b64_tr_b16 v[222:223], v241 offset:16128
	s_waitcnt lgkmcnt(10)
	v_mfma_f32_16x16x32_bf16 v[24:27], v[224:227], v[48:51], v[24:27]
	ds_read_b64_tr_b16 v[224:225], v241 offset:13856
	ds_read_b64_tr_b16 v[226:227], v241 offset:16160
	s_waitcnt lgkmcnt(10)
	v_mfma_f32_16x16x32_bf16 v[36:39], v[228:231], v[56:59], v[36:39]
	ds_read_b64_tr_b16 v[228:229], v241 offset:13888
	ds_read_b64_tr_b16 v[230:231], v241 offset:16192
	s_waitcnt lgkmcnt(10)
	v_mfma_f32_16x16x32_bf16 v[32:35], v[232:235], v[56:59], v[32:35]
	ds_read_b64_tr_b16 v[232:233], v241 offset:13920
	ds_read_b64_tr_b16 v[234:235], v241 offset:16224
	s_waitcnt lgkmcnt(10)
	v_mfma_f32_16x16x32_bf16 v[28:31], v[236:239], v[56:59], v[28:31]
	s_waitcnt lgkmcnt(8)
	v_mfma_f32_16x16x32_bf16 v[24:27], v[252:255], v[56:59], v[24:27]
	s_waitcnt lgkmcnt(6)
	v_mfma_f32_16x16x32_bf16 v[36:39], v[220:223], v[64:67], v[36:39]
	s_waitcnt lgkmcnt(4)
	v_mfma_f32_16x16x32_bf16 v[32:35], v[224:227], v[64:67], v[32:35]
	s_waitcnt lgkmcnt(2)
	v_mfma_f32_16x16x32_bf16 v[28:31], v[228:231], v[64:67], v[28:31]
	s_waitcnt lgkmcnt(0)
	v_mfma_f32_16x16x32_bf16 v[24:27], v[232:235], v[64:67], v[24:27]
	s_nop 7
	s_branch .LBB0_1170

.LBB0_1521:
	v_lshl_add_u32 v80, s6, 6, v123
	v_mad_u64_u32 v[192:193], s[0:1], v80, s51, v[116:117]
	ds_read_b128 v[64:67], v148 offset:2048
	ds_read_b128 v[68:71], v148 offset:2064
	ds_read_b128 v[72:75], v148 offset:2080
	ds_read_b128 v[76:79], v148 offset:2096
	ds_read_b128 v[80:83], v192 offset:55296
	ds_read_b128 v[84:87], v192 offset:55312
	v_add_u32_e32 v167, v116, v149
	ds_read_b128 v[88:91], v167
	ds_read_b128 v[92:95], v167 offset:16
	ds_read_b128 v[96:99], v167 offset:32
	ds_read_b128 v[100:103], v167 offset:48
	ds_read_b128 v[104:107], v192 offset:55568
	ds_read_b128 v[108:111], v192 offset:55584
	ds_read_b128 v[112:115], v167 offset:512
	ds_read_b128 v[132:135], v167 offset:528
	ds_read_b128 v[136:139], v167 offset:544
	ds_read_b128 v[140:143], v167 offset:560
	ds_read_b128 v[144:147], v192 offset:55840
	ds_read_b128 v[168:171], v192 offset:55856
	ds_read_b128 v[172:175], v167 offset:1024
	ds_read_b128 v[176:179], v167 offset:1040
	ds_read_b128 v[180:183], v167 offset:1056
	ds_read_b128 v[184:187], v167 offset:1072
	ds_read_b128 v[188:191], v192 offset:56112
	ds_read_b128 v[192:195], v192 offset:56128
	ds_read_b128 v[196:199], v167 offset:1536
	ds_read_b128 v[200:203], v167 offset:1552
	ds_read_b128 v[204:207], v167 offset:1568
	ds_read_b128 v[208:211], v167 offset:1584
	s_add_i32 s11, s6, s73
	s_waitcnt lgkmcnt(14)
	v_lshlrev_b32_e32 v212, 16, v80
	v_and_b32_e32 v213, 0xffff0000, v80
	v_lshlrev_b32_e32 v80, 16, v81
	v_and_b32_e32 v81, 0xffff0000, v81
	v_fma_f32 v66, v90, v80, v66
	v_fma_f32 v67, v91, v81, v67
	v_lshlrev_b32_e32 v80, 16, v105
	v_and_b32_e32 v81, 0xffff0000, v105
	v_fma_f32 v66, v114, v80, v66
	v_fma_f32 v67, v115, v81, v67
	s_waitcnt lgkmcnt(11)
	v_lshlrev_b32_e32 v80, 16, v145
	v_and_b32_e32 v81, 0xffff0000, v145
	s_waitcnt lgkmcnt(9)
	v_fma_f32 v66, v174, v80, v66
	v_fma_f32 v67, v175, v81, v67
	s_waitcnt lgkmcnt(5)
	v_lshlrev_b32_e32 v80, 16, v189
	v_and_b32_e32 v81, 0xffff0000, v189
	s_waitcnt lgkmcnt(3)
	v_fma_f32 v66, v198, v80, v66
	v_fma_f32 v67, v199, v81, v67
	v_lshlrev_b32_e32 v80, 16, v85
	v_and_b32_e32 v81, 0xffff0000, v85
	v_fma_f32 v74, v98, v80, v74
	v_fma_f32 v75, v99, v81, v75
	v_lshlrev_b32_e32 v80, 16, v109
	v_and_b32_e32 v81, 0xffff0000, v109
	v_fma_f32 v74, v138, v80, v74
	v_fma_f32 v75, v139, v81, v75
	v_lshlrev_b32_e32 v80, 16, v169
	v_and_b32_e32 v81, 0xffff0000, v169
	v_fma_f32 v74, v182, v80, v74
	v_fma_f32 v75, v183, v81, v75
	v_lshlrev_b32_e32 v80, 16, v193
	v_and_b32_e32 v81, 0xffff0000, v193
	s_waitcnt lgkmcnt(1)
	v_fma_f32 v74, v206, v80, v74
	v_fma_f32 v75, v207, v81, v75
	v_lshlrev_b32_e32 v80, 16, v82
	v_and_b32_e32 v81, 0xffff0000, v82
	v_fma_f32 v68, v92, v80, v68
	v_fma_f32 v69, v93, v81, v69
	v_lshlrev_b32_e32 v80, 16, v106
	v_and_b32_e32 v81, 0xffff0000, v106
	v_fma_f32 v68, v132, v80, v68
	v_fma_f32 v69, v133, v81, v69
	v_lshlrev_b32_e32 v80, 16, v146
	v_and_b32_e32 v81, 0xffff0000, v146
	v_fma_f32 v68, v176, v80, v68
	v_fma_f32 v69, v177, v81, v69
	v_lshlrev_b32_e32 v80, 16, v190
	v_and_b32_e32 v81, 0xffff0000, v190
	v_fma_f32 v68, v200, v80, v68
	v_fma_f32 v69, v201, v81, v69
	v_lshlrev_b32_e32 v80, 16, v86
	v_and_b32_e32 v81, 0xffff0000, v86
	v_fma_f32 v76, v100, v80, v76
	v_fma_f32 v77, v101, v81, v77
	v_lshlrev_b32_e32 v80, 16, v110
	v_and_b32_e32 v81, 0xffff0000, v110
	v_fma_f32 v76, v140, v80, v76
	v_fma_f32 v77, v141, v81, v77
	v_lshlrev_b32_e32 v80, 16, v170
	v_and_b32_e32 v81, 0xffff0000, v170
	v_fma_f32 v76, v184, v80, v76
	v_fma_f32 v77, v185, v81, v77
	v_lshlrev_b32_e32 v80, 16, v194
	v_and_b32_e32 v81, 0xffff0000, v194
	s_waitcnt lgkmcnt(0)
	v_fma_f32 v76, v208, v80, v76
	v_fma_f32 v77, v209, v81, v77
	v_lshlrev_b32_e32 v80, 16, v83
	v_and_b32_e32 v81, 0xffff0000, v83
	v_fma_f32 v64, v88, v212, v64
	v_fma_f32 v65, v89, v213, v65
	v_lshlrev_b32_e32 v88, 16, v104
	v_and_b32_e32 v89, 0xffff0000, v104
	v_fma_f32 v70, v94, v80, v70
	v_fma_f32 v71, v95, v81, v71
	v_lshlrev_b32_e32 v80, 16, v107
	v_and_b32_e32 v81, 0xffff0000, v107
	v_fma_f32 v64, v112, v88, v64
	v_fma_f32 v65, v113, v89, v65
	v_lshlrev_b32_e32 v88, 16, v144
	v_and_b32_e32 v89, 0xffff0000, v144
	v_fma_f32 v70, v134, v80, v70
	v_fma_f32 v71, v135, v81, v71
	v_lshlrev_b32_e32 v80, 16, v147
	v_and_b32_e32 v81, 0xffff0000, v147
	v_fma_f32 v64, v172, v88, v64
	v_fma_f32 v65, v173, v89, v65
	v_lshlrev_b32_e32 v88, 16, v188
	v_and_b32_e32 v89, 0xffff0000, v188
	v_fma_f32 v70, v178, v80, v70
	v_fma_f32 v71, v179, v81, v71
	v_lshlrev_b32_e32 v80, 16, v191
	v_and_b32_e32 v81, 0xffff0000, v191
	v_fma_f32 v64, v196, v88, v64
	v_fma_f32 v65, v197, v89, v65
	v_lshlrev_b32_e32 v88, 16, v84
	v_and_b32_e32 v89, 0xffff0000, v84
	v_fma_f32 v70, v202, v80, v70
	v_fma_f32 v71, v203, v81, v71
	v_lshlrev_b32_e32 v80, 16, v87
	v_and_b32_e32 v81, 0xffff0000, v87
	v_fma_f32 v72, v96, v88, v72
	v_fma_f32 v73, v97, v89, v73
	v_lshlrev_b32_e32 v88, 16, v108
	v_and_b32_e32 v89, 0xffff0000, v108
	v_fma_f32 v78, v102, v80, v78
	v_fma_f32 v79, v103, v81, v79
	v_lshlrev_b32_e32 v80, 16, v111
	v_and_b32_e32 v81, 0xffff0000, v111
	v_fma_f32 v72, v136, v88, v72
	v_fma_f32 v73, v137, v89, v73
	v_lshlrev_b32_e32 v88, 16, v168
	v_and_b32_e32 v89, 0xffff0000, v168
	v_fma_f32 v78, v142, v80, v78
	v_fma_f32 v79, v143, v81, v79
	v_lshlrev_b32_e32 v80, 16, v171
	v_and_b32_e32 v81, 0xffff0000, v171
	v_fma_f32 v72, v180, v88, v72
	v_fma_f32 v73, v181, v89, v73
	v_lshlrev_b32_e32 v88, 16, v192
	v_and_b32_e32 v89, 0xffff0000, v192
	v_fma_f32 v78, v186, v80, v78
	v_fma_f32 v79, v187, v81, v79
	v_lshlrev_b32_e32 v80, 16, v195
	v_and_b32_e32 v81, 0xffff0000, v195
	v_fma_f32 v72, v204, v88, v72
	v_fma_f32 v73, v205, v89, v73
	v_fma_f32 v78, v210, v80, v78
	v_fma_f32 v79, v211, v81, v79
	ds_write_b128 v150, v[64:67] offset:4096
	ds_write_b128 v150, v[68:71] offset:4112
	ds_write_b128 v150, v[72:75] offset:4128
	ds_write_b128 v150, v[76:79] offset:4144
	v_cvt_pk_bf16_f32 v64, v64, v65
	v_cvt_pk_bf16_f32 v65, v66, v67
	v_cvt_pk_bf16_f32 v66, v68, v69
	v_cvt_pk_bf16_f32 v67, v70, v71
	v_cvt_pk_bf16_f32 v72, v72, v73
	v_cvt_pk_bf16_f32 v73, v74, v75
	v_cvt_pk_bf16_f32 v74, v76, v77
	v_cvt_pk_bf16_f32 v75, v78, v79
	ds_write_b128 v151, v[64:67] offset:37888
	ds_write_b128 v151, v[72:75] offset:37904
	s_waitcnt lgkmcnt(0)
	s_barrier
	ds_read_b128 v[64:67], v159 offset:37888
	ds_read_b128 v[68:71], v159 offset:37952
	ds_read_b128 v[84:87], v159 offset:42240
	ds_read_b128 v[88:91], v159 offset:42304
	ds_read_b128 v[104:107], v159 offset:46592
	ds_read_b128 v[108:111], v159 offset:46656
	ds_read_b128 v[140:143], v159 offset:50944
	ds_read_b128 v[144:147], v159 offset:51008
	s_waitcnt lgkmcnt(7)
	v_mfma_f32_16x16x32_bf16 v[72:75], v[64:67], v[0:3], 0
	v_mfma_f32_16x16x32_bf16 v[76:79], v[64:67], v[20:23], 0
	v_mfma_f32_16x16x32_bf16 v[80:83], v[64:67], v[36:39], 0
	v_mfma_f32_16x16x32_bf16 v[64:67], v[64:67], v[56:59], 0
	s_waitcnt lgkmcnt(5)
	v_mfma_f32_16x16x32_bf16 v[92:95], v[84:87], v[0:3], 0
	v_mfma_f32_16x16x32_bf16 v[96:99], v[84:87], v[20:23], 0
	v_mfma_f32_16x16x32_bf16 v[100:103], v[84:87], v[36:39], 0
	v_mfma_f32_16x16x32_bf16 v[84:87], v[84:87], v[56:59], 0
	s_waitcnt lgkmcnt(3)
	v_mfma_f32_16x16x32_bf16 v[112:115], v[104:107], v[0:3], 0
	v_mfma_f32_16x16x32_bf16 v[132:135], v[104:107], v[20:23], 0
	v_mfma_f32_16x16x32_bf16 v[136:139], v[104:107], v[36:39], 0
	v_mfma_f32_16x16x32_bf16 v[104:107], v[104:107], v[56:59], 0
	s_waitcnt lgkmcnt(1)
	v_mfma_f32_16x16x32_bf16 v[168:171], v[140:143], v[0:3], 0
	v_mfma_f32_16x16x32_bf16 v[172:175], v[140:143], v[20:23], 0
	v_mfma_f32_16x16x32_bf16 v[176:179], v[140:143], v[36:39], 0
	v_mfma_f32_16x16x32_bf16 v[140:143], v[140:143], v[56:59], 0
	v_mfma_f32_16x16x32_bf16 v[72:75], v[68:71], v[4:7], v[72:75]
	v_mfma_f32_16x16x32_bf16 v[76:79], v[68:71], v[16:19], v[76:79]
	v_mfma_f32_16x16x32_bf16 v[80:83], v[68:71], v[32:35], v[80:83]
	v_mfma_f32_16x16x32_bf16 v[64:67], v[68:71], v[48:51], v[64:67]
	v_mfma_f32_16x16x32_bf16 v[68:71], v[88:91], v[4:7], v[92:95]
	v_mfma_f32_16x16x32_bf16 v[92:95], v[88:91], v[16:19], v[96:99]
	v_mfma_f32_16x16x32_bf16 v[96:99], v[88:91], v[32:35], v[100:103]
	v_mfma_f32_16x16x32_bf16 v[84:87], v[88:91], v[48:51], v[84:87]
	v_mfma_f32_16x16x32_bf16 v[88:91], v[108:111], v[4:7], v[112:115]
	v_mfma_f32_16x16x32_bf16 v[100:103], v[108:111], v[16:19], v[132:135]
	v_mfma_f32_16x16x32_bf16 v[112:115], v[108:111], v[32:35], v[136:139]
	v_mfma_f32_16x16x32_bf16 v[104:107], v[108:111], v[48:51], v[104:107]
	s_waitcnt lgkmcnt(0)
	v_mfma_f32_16x16x32_bf16 v[108:111], v[144:147], v[4:7], v[168:171]
	v_mfma_f32_16x16x32_bf16 v[132:135], v[144:147], v[16:19], v[172:175]
	v_mfma_f32_16x16x32_bf16 v[136:139], v[144:147], v[32:35], v[176:179]
	v_mfma_f32_16x16x32_bf16 v[140:143], v[144:147], v[48:51], v[140:143]
	ds_read_b128 v[144:147], v159 offset:38016
	ds_read_b128 v[168:171], v159 offset:38080
	s_waitcnt lgkmcnt(1)
	v_mfma_f32_16x16x32_bf16 v[72:75], v[144:147], v[8:11], v[72:75]
	v_mfma_f32_16x16x32_bf16 v[76:79], v[144:147], v[24:27], v[76:79]
	v_mfma_f32_16x16x32_bf16 v[80:83], v[144:147], v[40:43], v[80:83]
	v_mfma_f32_16x16x32_bf16 v[64:67], v[144:147], v[52:55], v[64:67]
	ds_read_b128 v[144:147], v159 offset:42368
	ds_read_b128 v[172:175], v159 offset:42432
	s_waitcnt lgkmcnt(1)
	v_mfma_f32_16x16x32_bf16 v[176:179], v[144:147], v[8:11], v[68:71]
	s_nop 2
	ds_read_b128 v[68:71], v159 offset:46720
	ds_read_b128 v[188:191], v159 offset:46784
	v_mfma_f32_16x16x32_bf16 v[180:183], v[144:147], v[24:27], v[92:95]
	v_mfma_f32_16x16x32_bf16 v[184:187], v[144:147], v[40:43], v[96:99]
	v_mfma_f32_16x16x32_bf16 v[84:87], v[144:147], v[52:55], v[84:87]
	s_waitcnt lgkmcnt(1)
	v_mfma_f32_16x16x32_bf16 v[88:91], v[68:71], v[8:11], v[88:91]
	v_mfma_f32_16x16x32_bf16 v[144:147], v[68:71], v[24:27], v[100:103]
	v_mfma_f32_16x16x32_bf16 v[192:195], v[68:71], v[40:43], v[112:115]
	v_mfma_f32_16x16x32_bf16 v[196:199], v[68:71], v[52:55], v[104:107]
	ds_read_b128 v[68:71], v159 offset:51072
	ds_read_b128 v[92:95], v159 offset:51136
	s_waitcnt lgkmcnt(1)
	v_mfma_f32_16x16x32_bf16 v[200:203], v[68:71], v[8:11], v[108:111]
	v_mfma_f32_16x16x32_bf16 v[204:207], v[68:71], v[24:27], v[132:135]
	v_mfma_f32_16x16x32_bf16 v[208:211], v[68:71], v[40:43], v[136:139]
	v_mfma_f32_16x16x32_bf16 v[96:99], v[68:71], v[52:55], v[140:143]
	v_mfma_f32_16x16x32_bf16 v[68:71], v[168:171], v[44:47], v[80:83]
	s_nop 2
	v_add_u32_e32 v80, 0x3000, v160
	v_mfma_f32_16x16x32_bf16 v[112:115], v[172:175], v[12:15], v[176:179]
	ds_read2_b32 v[136:137], v80 offset0:64 offset1:196
	v_add_u32_e32 v80, 0x3400, v160
	ds_read2_b32 v[138:139], v80 offset0:72 offset1:204
	s_waitcnt lgkmcnt(2)
	v_mfma_f32_16x16x32_bf16 v[176:179], v[92:95], v[12:15], v[200:203]
	v_add_u32_e32 v80, 0x5200, v160
	ds_read2_b32 v[140:141], v80 offset1:132
	v_add_u32_e32 v80, 0x5600, v160
	v_mfma_f32_16x16x32_bf16 v[104:107], v[168:171], v[12:15], v[72:75]
	ds_read2_b32 v[142:143], v80 offset0:8 offset1:140
	v_add_u32_e32 v80, 0x7200, v160
	s_nop 1
	v_add_f32_e32 v176, v127, v176
	v_add_u32_e32 v72, 0x1000, v160
	ds_read2_b32 v[132:133], v72 offset1:132
	v_add_u32_e32 v72, 0x1400, v160
	v_mfma_f32_16x16x32_bf16 v[100:103], v[168:171], v[28:31], v[76:79]
	ds_read2_b32 v[134:135], v72 offset0:8 offset1:140
	v_exp_f32_e32 v176, v176
	v_add_f32_e32 v177, v127, v177
	v_mfma_f32_16x16x32_bf16 v[108:111], v[172:175], v[28:31], v[180:183]
	v_exp_f32_e32 v177, v177
	v_add_f32_e32 v176, 1.0, v176
	v_rcp_f32_e32 v176, v176
	v_mfma_f32_16x16x32_bf16 v[76:79], v[172:175], v[44:47], v[184:187]
	v_add_f32_e32 v177, 1.0, v177
	v_rcp_f32_e32 v177, v177
	v_mul_f32_e32 v176, v131, v176
	v_mfma_f32_16x16x32_bf16 v[72:75], v[172:175], v[60:63], v[84:87]
	v_exp_f32_e32 v176, v176
	v_mul_f32_e32 v177, v131, v177
	v_exp_f32_e32 v177, v177
	v_mfma_f32_16x16x32_bf16 v[172:175], v[188:191], v[28:31], v[144:147]
	v_add_u32_e32 v85, 0x7600, v160
	v_add_f32_e32 v114, v127, v114
	v_exp_f32_e32 v114, v114
	ds_read2_b32 v[144:145], v80 offset0:64 offset1:196
	v_add_f32_e32 v80, v127, v179
	v_exp_f32_e32 v84, v80
	v_mfma_f32_16x16x32_bf16 v[64:67], v[168:171], v[60:63], v[64:67]
	ds_read2_b32 v[146:147], v85 offset0:72 offset1:204
	v_add_f32_e32 v174, v129, v174
	v_add_f32_e32 v84, 1.0, v84
	v_rcp_f32_e32 v84, v84
	v_mfma_f32_16x16x32_bf16 v[168:171], v[188:191], v[12:15], v[88:91]
	v_exp_f32_e32 v174, v174
	v_add_f32_e32 v175, v129, v175
	v_exp_f32_e32 v175, v175
	v_mul_f32_e32 v88, v131, v84
	v_exp_f32_e32 v179, v88
	v_add_f32_e32 v88, v127, v178
	v_exp_f32_e32 v178, v88
	v_mfma_f32_16x16x32_bf16 v[180:183], v[92:95], v[28:31], v[204:207]
	v_add_f32_e32 v170, v127, v170
	v_exp_f32_e32 v170, v170
	v_add_f32_e32 v178, 1.0, v178
	v_rcp_f32_e32 v178, v178
	v_add_f32_e32 v171, v127, v171
	s_nop 2
	v_add_f32_e32 v182, v129, v182
	v_exp_f32_e32 v182, v182
	v_mul_f32_e32 v178, v131, v178
	v_exp_f32_e32 v178, v178
	v_add_f32_e32 v85, v129, v183
	v_exp_f32_e32 v167, v85
	v_exp_f32_e32 v171, v171
	v_fma_f32 v184, -v178, v178, 1.0
	v_add_f32_e32 v182, 1.0, v182
	v_max_f32_e32 v184, 0, v184
	v_fma_f32 v183, -v179, v179, 1.0
	v_rcp_f32_e32 v182, v182
	v_sqrt_f32_e32 v184, v184
	v_add_f32_e32 v180, v129, v180
	v_add_f32_e32 v170, 1.0, v170
	v_add_f32_e32 v167, 1.0, v167
	v_max_f32_e32 v183, 0, v183
	v_exp_f32_e32 v180, v180
	v_rcp_f32_e32 v170, v170
	v_add_f32_e32 v168, v127, v168
	v_rcp_f32_e32 v167, v167
	v_sqrt_f32_e32 v183, v183
	v_add_f32_e32 v181, v129, v181
	v_add_f32_e32 v171, 1.0, v171
	v_exp_f32_e32 v168, v168
	v_exp_f32_e32 v181, v181
	v_rcp_f32_e32 v171, v171
	v_add_f32_e32 v169, v127, v169
	v_mul_f32_e32 v182, v182, v184
	v_fma_f32 v184, -v176, v176, 1.0
	v_exp_f32_e32 v169, v169
	v_add_f32_e32 v180, 1.0, v180
	v_max_f32_e32 v184, 0, v184
	v_mul_f32_e32 v170, v131, v170
	v_mul_f32_e32 v167, v167, v183
	v_fma_f32 v183, -v177, v177, 1.0
	v_rcp_f32_e32 v180, v180
	v_sqrt_f32_e32 v184, v184
	v_exp_f32_e32 v170, v170
	v_add_f32_e32 v168, 1.0, v168
	v_add_f32_e32 v181, 1.0, v181
	v_max_f32_e32 v183, 0, v183
	v_mul_f32_e32 v171, v131, v171
	v_rcp_f32_e32 v168, v168
	v_rcp_f32_e32 v181, v181
	v_sqrt_f32_e32 v183, v183
	v_exp_f32_e32 v171, v171
	v_add_f32_e32 v169, 1.0, v169
	v_rcp_f32_e32 v169, v169
	v_add_f32_e32 v115, v127, v115
	v_mul_f32_e32 v180, v180, v184
	v_fma_f32 v184, -v170, v170, 1.0
	v_exp_f32_e32 v115, v115
	v_add_f32_e32 v174, 1.0, v174
	v_max_f32_e32 v184, 0, v184
	v_mul_f32_e32 v168, v131, v168
	v_mul_f32_e32 v181, v181, v183
	v_fma_f32 v183, -v171, v171, 1.0
	v_rcp_f32_e32 v174, v174
	v_sqrt_f32_e32 v184, v184
	v_add_f32_e32 v172, v129, v172
	v_exp_f32_e32 v168, v168
	v_add_f32_e32 v114, 1.0, v114
	v_add_f32_e32 v175, 1.0, v175
	v_max_f32_e32 v183, 0, v183
	v_mul_f32_e32 v169, v131, v169
	v_exp_f32_e32 v172, v172
	v_rcp_f32_e32 v114, v114
	v_add_f32_e32 v112, v127, v112
	v_rcp_f32_e32 v175, v175
	v_sqrt_f32_e32 v183, v183
	v_add_f32_e32 v173, v129, v173
	v_exp_f32_e32 v169, v169
	v_add_f32_e32 v115, 1.0, v115
	v_exp_f32_e32 v112, v112
	v_add_f32_e32 v104, v127, v104
	v_exp_f32_e32 v173, v173
	v_rcp_f32_e32 v115, v115
	v_add_f32_e32 v113, v127, v113
	v_exp_f32_e32 v104, v104
	v_mul_f32_e32 v174, v174, v184
	v_fma_f32 v184, -v168, v168, 1.0
	v_exp_f32_e32 v113, v113
	v_add_f32_e32 v172, 1.0, v172
	v_max_f32_e32 v184, 0, v184
	v_mul_f32_e32 v114, v131, v114
	v_add_f32_e32 v105, v127, v105
	v_mul_f32_e32 v175, v175, v183
	v_fma_f32 v183, -v169, v169, 1.0
	v_rcp_f32_e32 v172, v172
	v_sqrt_f32_e32 v184, v184
	v_add_f32_e32 v110, v129, v110
	v_exp_f32_e32 v114, v114
	v_add_f32_e32 v112, 1.0, v112
	v_exp_f32_e32 v105, v105
	v_add_f32_e32 v173, 1.0, v173
	v_max_f32_e32 v183, 0, v183
	v_mul_f32_e32 v115, v131, v115
	v_exp_f32_e32 v110, v110
	v_rcp_f32_e32 v112, v112
	v_add_f32_e32 v106, v127, v106
	v_add_f32_e32 v104, 1.0, v104
	v_rcp_f32_e32 v173, v173
	v_sqrt_f32_e32 v183, v183
	v_add_f32_e32 v111, v129, v111
	v_exp_f32_e32 v115, v115
	v_add_f32_e32 v113, 1.0, v113
	v_exp_f32_e32 v106, v106
	v_rcp_f32_e32 v104, v104
	v_exp_f32_e32 v111, v111
	v_rcp_f32_e32 v113, v113
	v_add_f32_e32 v107, v127, v107
	v_mul_f32_e32 v172, v172, v184
	v_fma_f32 v184, -v114, v114, 1.0
	v_exp_f32_e32 v107, v107
	v_add_f32_e32 v105, 1.0, v105
	v_add_f32_e32 v110, 1.0, v110
	v_max_f32_e32 v184, 0, v184
	v_mul_f32_e32 v112, v131, v112
	v_rcp_f32_e32 v105, v105
	v_mul_f32_e32 v173, v173, v183
	v_fma_f32 v183, -v115, v115, 1.0
	v_rcp_f32_e32 v110, v110
	v_sqrt_f32_e32 v184, v184
	v_add_f32_e32 v108, v129, v108
	v_exp_f32_e32 v112, v112
	v_add_f32_e32 v106, 1.0, v106
	v_mul_f32_e32 v104, v131, v104
	v_add_f32_e32 v111, 1.0, v111
	v_max_f32_e32 v183, 0, v183
	v_mul_f32_e32 v113, v131, v113
	v_exp_f32_e32 v108, v108
	v_rcp_f32_e32 v106, v106
	v_add_f32_e32 v100, v129, v100
	v_exp_f32_e32 v104, v104
	v_rcp_f32_e32 v111, v111
	v_sqrt_f32_e32 v183, v183
	v_add_f32_e32 v109, v129, v109
	v_exp_f32_e32 v113, v113
	v_add_f32_e32 v107, 1.0, v107
	v_exp_f32_e32 v100, v100
	v_exp_f32_e32 v109, v109
	v_rcp_f32_e32 v107, v107
	v_mul_f32_e32 v105, v131, v105
	v_mul_f32_e32 v110, v110, v184
	v_fma_f32 v184, -v112, v112, 1.0
	v_add_f32_e32 v101, v129, v101
	v_exp_f32_e32 v105, v105
	v_add_f32_e32 v108, 1.0, v108
	v_max_f32_e32 v184, 0, v184
	v_mul_f32_e32 v106, v131, v106
	v_exp_f32_e32 v101, v101
	v_fma_f32 v186, -v104, v104, 1.0
	v_mul_f32_e32 v111, v111, v183
	v_fma_f32 v183, -v113, v113, 1.0
	v_rcp_f32_e32 v108, v108
	v_sqrt_f32_e32 v184, v184
	v_add_f32_e32 v102, v129, v102
	v_exp_f32_e32 v106, v106
	v_add_f32_e32 v100, 1.0, v100
	v_max_f32_e32 v186, 0, v186
	v_add_f32_e32 v109, 1.0, v109
	v_max_f32_e32 v183, 0, v183
	v_mul_f32_e32 v107, v131, v107
	v_exp_f32_e32 v102, v102
	v_rcp_f32_e32 v100, v100
	v_sqrt_f32_e32 v186, v186
	v_rcp_f32_e32 v109, v109
	v_sqrt_f32_e32 v183, v183
	v_add_f32_e32 v103, v129, v103
	v_exp_f32_e32 v107, v107
	v_fma_f32 v185, -v105, v105, 1.0
	v_exp_f32_e32 v103, v103
	v_add_f32_e32 v101, 1.0, v101
	v_max_f32_e32 v185, 0, v185
	v_mul_f32_e32 v108, v108, v184
	v_fma_f32 v184, -v106, v106, 1.0
	v_rcp_f32_e32 v101, v101
	v_sqrt_f32_e32 v185, v185
	v_add_f32_e32 v102, 1.0, v102
	v_max_f32_e32 v184, 0, v184
	v_mul_f32_e32 v100, v100, v186
	v_mul_f32_e32 v109, v109, v183
	v_fma_f32 v183, -v107, v107, 1.0
	v_rcp_f32_e32 v102, v102
	v_sqrt_f32_e32 v184, v184
	s_waitcnt lgkmcnt(3)
	v_mul_f32_e32 v100, v100, v132
	v_add_f32_e32 v103, 1.0, v103
	v_max_f32_e32 v183, 0, v183
	v_fmac_f32_e32 v100, 0, v104
	v_rcp_f32_e32 v103, v103
	v_sqrt_f32_e32 v183, v183
	v_mul_f32_e32 v101, v101, v185
	v_mul_f32_e32 v100, v105, v100
	v_fmac_f32_e32 v100, v101, v133
	v_mul_f32_e32 v102, v102, v184
	v_mul_f32_e32 v100, v106, v100
	s_waitcnt lgkmcnt(2)
	v_fmac_f32_e32 v100, v102, v134
	v_mul_f32_e32 v103, v103, v183
	v_mul_f32_e32 v100, v107, v100
	v_fmac_f32_e32 v100, v103, v135
	v_mul_f32_e32 v100, v112, v100
	v_fmac_f32_e32 v100, v108, v136
	v_mul_f32_e32 v100, v113, v100
	v_fmac_f32_e32 v100, v109, v137
	v_mul_f32_e32 v100, v114, v100
	v_fmac_f32_e32 v100, v110, v138
	v_mul_f32_e32 v100, v115, v100
	v_fmac_f32_e32 v100, v111, v139
	v_mul_f32_e32 v100, v168, v100
	v_mul_f32_e32 v101, v104, v105
	v_fmac_f32_e32 v100, v172, v140
	v_mul_f32_e32 v101, v106, v101
	v_mul_f32_e32 v100, v169, v100
	v_mul_f32_e32 v101, v107, v101
	v_fmac_f32_e32 v100, v173, v141
	v_mul_f32_e32 v101, v101, v112
	v_mul_f32_e32 v100, v170, v100
	v_mul_f32_e32 v101, v113, v101
	v_fmac_f32_e32 v100, v174, v142
	v_mul_f32_e32 v101, v114, v101
	v_mul_f32_e32 v100, v171, v100
	v_mul_f32_e32 v101, v115, v101
	v_fmac_f32_e32 v100, v175, v143
	v_mul_f32_e32 v101, v101, v168
	v_mul_f32_e32 v100, v176, v100
	v_mul_f32_e32 v101, v169, v101
	s_waitcnt lgkmcnt(1)
	v_fmac_f32_e32 v100, v180, v144
	v_mul_f32_e32 v101, v170, v101
	v_mul_f32_e32 v100, v177, v100
	v_mul_f32_e32 v101, v171, v101
	v_fmac_f32_e32 v100, v181, v145
	v_mul_f32_e32 v101, v101, v176
	v_mul_f32_e32 v100, v178, v100
	v_mul_f32_e32 v101, v177, v101
	s_waitcnt lgkmcnt(0)
	v_fmac_f32_e32 v100, v182, v146
	v_mul_f32_e32 v101, v178, v101
	v_mul_f32_e32 v104, v179, v100
	v_fmac_f32_e32 v104, v167, v147
	v_mul_f32_e32 v103, v179, v101
	ds_bpermute_b32 v100, v162, v103
	ds_bpermute_b32 v102, v164, v103
	ds_bpermute_b32 v101, v165, v103
	ds_bpermute_b32 v103, v166, v103
	ds_bpermute_b32 v107, v162, v104
	ds_bpermute_b32 v106, v164, v104
	ds_bpermute_b32 v105, v165, v104
	ds_bpermute_b32 v104, v166, v104
	v_mfma_f32_16x16x32_bf16 v[80:83], v[188:191], v[44:47], v[192:195]
	v_mfma_f32_16x16x32_bf16 v[84:87], v[188:191], v[60:63], v[196:199]
	v_mfma_f32_16x16x32_bf16 v[88:91], v[92:95], v[44:47], v[208:211]
	v_mfma_f32_16x16x32_bf16 v[92:95], v[92:95], v[60:63], v[96:99]
	s_and_saveexec_b64 s[0:1], s[4:5]
	s_cbranch_execz .LBB0_1523
	s_waitcnt lgkmcnt(3)
	v_fmac_f32_e32 v107, 0, v100
	s_waitcnt lgkmcnt(2)
	v_fmac_f32_e32 v106, v107, v102
	s_waitcnt lgkmcnt(1)
	v_fmac_f32_e32 v105, v106, v101
	v_mul_f32_e64 v96, v100, v102
	v_mul_f32_e64 v97, v101, v103
	s_add_i32 s12, s11, s9
	s_waitcnt lgkmcnt(0)
	v_fmac_f32_e32 v104, v105, v103
	v_mad_i64_i32 v[98:99], s[12:13], s12, v163, v[124:125]
	v_pk_mul_f32 v[96:97], v[96:97], v[96:97] op_sel:[0,1] op_sel_hi:[1,0]
	v_lshl_add_u64 v[98:99], v[98:99], 3, s[36:37]
	v_mov_b32_e32 v97, v104
	global_store_dwordx2 v[98:99], v[96:97], off
.LBB0_1523:
	s_or_b64 exec, exec, s[0:1]
	s_nop 3
	v_add_f32_e32 v91, v126, v91
	v_exp_f32_e32 v91, v91
	v_add_f32_e32 v90, v126, v90
	v_exp_f32_e32 v90, v90
	v_add_f32_e32 v95, v128, v95
	v_add_f32_e32 v91, 1.0, v91
	v_rcp_f32_e32 v91, v91
	v_add_f32_e32 v90, 1.0, v90
	v_exp_f32_e32 v95, v95
	v_rcp_f32_e32 v90, v90
	v_mul_f32_e32 v91, v130, v91
	v_exp_f32_e32 v91, v91
	v_add_f32_e32 v89, v126, v89
	v_exp_f32_e32 v89, v89
	v_add_f32_e32 v88, v126, v88
	v_fma_f32 v96, -v91, v91, 1.0
	v_exp_f32_e32 v88, v88
	v_add_f32_e32 v95, 1.0, v95
	v_max_f32_e32 v96, 0, v96
	v_mul_f32_e32 v90, v130, v90
	v_add_f32_e32 v94, v128, v94
	v_rcp_f32_e32 v95, v95
	v_sqrt_f32_e32 v96, v96
	v_exp_f32_e32 v90, v90
	v_add_f32_e32 v89, 1.0, v89
	v_exp_f32_e32 v94, v94
	v_rcp_f32_e32 v89, v89
	v_add_f32_e32 v83, v126, v83
	v_add_f32_e32 v88, 1.0, v88
	v_exp_f32_e32 v83, v83
	v_rcp_f32_e32 v88, v88
	v_add_f32_e32 v82, v126, v82
	v_mul_f32_e32 v95, v95, v96
	v_fma_f32 v96, -v90, v90, 1.0
	v_exp_f32_e32 v82, v82
	v_add_f32_e32 v94, 1.0, v94
	v_max_f32_e32 v96, 0, v96
	v_mul_f32_e32 v89, v130, v89
	v_rcp_f32_e32 v94, v94
	v_sqrt_f32_e32 v96, v96
	v_add_f32_e32 v93, v128, v93
	v_exp_f32_e32 v89, v89
	v_add_f32_e32 v83, 1.0, v83
	v_exp_f32_e32 v93, v93
	v_mul_f32_e32 v88, v130, v88
	v_rcp_f32_e32 v83, v83
	v_add_f32_e32 v81, v126, v81
	v_add_f32_e32 v92, v128, v92
	v_exp_f32_e32 v88, v88
	v_add_f32_e32 v82, 1.0, v82
	v_exp_f32_e32 v81, v81
	v_exp_f32_e32 v92, v92
	v_rcp_f32_e32 v82, v82
	v_add_f32_e32 v80, v126, v80
	v_mul_f32_e32 v94, v94, v96
	v_fma_f32 v96, -v89, v89, 1.0
	v_exp_f32_e32 v80, v80
	v_add_f32_e32 v93, 1.0, v93
	v_max_f32_e32 v96, 0, v96
	v_mul_f32_e32 v83, v130, v83
	v_rcp_f32_e32 v93, v93
	v_sqrt_f32_e32 v96, v96
	v_fma_f32 v97, -v88, v88, 1.0
	v_add_f32_e32 v87, v128, v87
	v_exp_f32_e32 v83, v83
	v_add_f32_e32 v81, 1.0, v81
	v_add_f32_e32 v92, 1.0, v92
	v_max_f32_e32 v97, 0, v97
	v_exp_f32_e32 v87, v87
	v_mul_f32_e32 v82, v130, v82
	v_rcp_f32_e32 v81, v81
	v_add_f32_e32 v79, v126, v79
	v_rcp_f32_e32 v92, v92
	v_sqrt_f32_e32 v97, v97
	v_add_f32_e32 v86, v128, v86
	v_exp_f32_e32 v82, v82
	v_add_f32_e32 v80, 1.0, v80
	v_exp_f32_e32 v79, v79
	v_exp_f32_e32 v86, v86
	v_rcp_f32_e32 v80, v80
	v_add_f32_e32 v78, v126, v78
	v_mul_f32_e32 v93, v93, v96
	v_fma_f32 v96, -v83, v83, 1.0
	v_exp_f32_e32 v78, v78
	v_add_f32_e32 v87, 1.0, v87
	v_max_f32_e32 v96, 0, v96
	v_mul_f32_e32 v81, v130, v81
	v_mul_f32_e32 v92, v92, v97
	v_rcp_f32_e32 v87, v87
	v_sqrt_f32_e32 v96, v96
	v_fma_f32 v97, -v82, v82, 1.0
	v_add_f32_e32 v85, v128, v85
	v_exp_f32_e32 v81, v81
	v_add_f32_e32 v79, 1.0, v79
	v_add_f32_e32 v86, 1.0, v86
	v_max_f32_e32 v97, 0, v97
	v_exp_f32_e32 v85, v85
	v_mul_f32_e32 v80, v130, v80
	v_rcp_f32_e32 v79, v79
	v_add_f32_e32 v77, v126, v77
	v_rcp_f32_e32 v86, v86
	v_sqrt_f32_e32 v97, v97
	v_add_f32_e32 v84, v128, v84
	v_exp_f32_e32 v80, v80
	v_add_f32_e32 v78, 1.0, v78
	v_exp_f32_e32 v77, v77
	v_exp_f32_e32 v84, v84
	v_rcp_f32_e32 v78, v78
	v_add_f32_e32 v76, v126, v76
	v_mul_f32_e32 v95, v95, v147
	v_mul_f32_e32 v87, v87, v96
	v_fma_f32 v96, -v81, v81, 1.0
	v_exp_f32_e32 v76, v76
	v_add_f32_e32 v85, 1.0, v85
	v_max_f32_e32 v96, 0, v96
	v_mul_f32_e32 v79, v130, v79
	v_fmac_f32_e32 v95, 0, v91
	v_mul_f32_e32 v86, v86, v97
	v_rcp_f32_e32 v85, v85
	v_sqrt_f32_e32 v96, v96
	v_fma_f32 v97, -v80, v80, 1.0
	v_add_f32_e32 v75, v128, v75
	v_exp_f32_e32 v79, v79
	v_add_f32_e32 v77, 1.0, v77
	v_mul_f32_e32 v95, v90, v95
	v_add_f32_e32 v84, 1.0, v84
	v_max_f32_e32 v97, 0, v97
	v_exp_f32_e32 v75, v75
	v_mul_f32_e32 v78, v130, v78
	v_rcp_f32_e32 v77, v77
	v_add_f32_e32 v71, v126, v71
	v_fmac_f32_e32 v95, v94, v146
	v_rcp_f32_e32 v84, v84
	v_sqrt_f32_e32 v97, v97
	v_add_f32_e32 v74, v128, v74
	v_exp_f32_e32 v78, v78
	v_add_f32_e32 v76, 1.0, v76
	v_exp_f32_e32 v71, v71
	v_mul_f32_e32 v90, v91, v90
	v_mul_f32_e32 v91, v89, v95
	v_exp_f32_e32 v74, v74
	v_rcp_f32_e32 v76, v76
	v_add_f32_e32 v70, v126, v70
	v_fmac_f32_e32 v91, v93, v145
	v_mul_f32_e32 v85, v85, v96
	v_fma_f32 v96, -v79, v79, 1.0
	v_exp_f32_e32 v70, v70
	v_mul_f32_e32 v89, v89, v90
	v_mul_f32_e32 v90, v88, v91
	v_add_f32_e32 v75, 1.0, v75
	v_max_f32_e32 v96, 0, v96
	v_mul_f32_e32 v77, v130, v77
	v_add_f32_e32 v69, v126, v69
	v_fmac_f32_e32 v90, v92, v144
	v_mul_f32_e32 v84, v84, v97
	v_rcp_f32_e32 v75, v75
	v_sqrt_f32_e32 v96, v96
	v_fma_f32 v97, -v78, v78, 1.0
	v_add_f32_e32 v73, v128, v73
	v_exp_f32_e32 v77, v77
	v_add_f32_e32 v71, 1.0, v71
	v_exp_f32_e32 v69, v69
	v_mul_f32_e32 v88, v88, v89
	v_mul_f32_e32 v89, v83, v90
	v_add_f32_e32 v74, 1.0, v74
	v_max_f32_e32 v97, 0, v97
	v_exp_f32_e32 v73, v73
	v_mul_f32_e32 v76, v130, v76
	v_rcp_f32_e32 v71, v71
	v_add_f32_e32 v68, v126, v68
	v_fmac_f32_e32 v89, v87, v143
	v_rcp_f32_e32 v74, v74
	v_sqrt_f32_e32 v97, v97
	v_add_f32_e32 v72, v128, v72
	v_exp_f32_e32 v76, v76
	v_add_f32_e32 v70, 1.0, v70
	v_exp_f32_e32 v68, v68
	v_mul_f32_e32 v87, v82, v89
	v_exp_f32_e32 v72, v72
	v_rcp_f32_e32 v70, v70
	v_mul_f32_e32 v83, v83, v88
	v_fmac_f32_e32 v87, v86, v142
	v_mul_f32_e32 v75, v75, v96
	v_fma_f32 v96, -v77, v77, 1.0
	v_add_f32_e32 v69, 1.0, v69
	v_mul_f32_e32 v82, v82, v83
	v_mul_f32_e32 v83, v81, v87
	v_add_f32_e32 v73, 1.0, v73
	v_max_f32_e32 v96, 0, v96
	v_mul_f32_e32 v71, v130, v71
	v_rcp_f32_e32 v69, v69
	v_fmac_f32_e32 v83, v85, v141
	v_mul_f32_e32 v74, v74, v97
	v_rcp_f32_e32 v73, v73
	v_sqrt_f32_e32 v96, v96
	v_fma_f32 v97, -v76, v76, 1.0
	v_add_f32_e32 v67, v128, v67
	v_exp_f32_e32 v71, v71
	v_add_f32_e32 v68, 1.0, v68
	v_mul_f32_e32 v81, v81, v82
	v_mul_f32_e32 v82, v80, v83
	v_add_f32_e32 v72, 1.0, v72
	v_max_f32_e32 v97, 0, v97
	v_exp_f32_e32 v67, v67
	v_mul_f32_e32 v70, v130, v70
	v_rcp_f32_e32 v68, v68
	v_fmac_f32_e32 v82, v84, v140
	v_rcp_f32_e32 v72, v72
	v_sqrt_f32_e32 v97, v97
	v_add_f32_e32 v66, v128, v66
	v_exp_f32_e32 v70, v70
	v_mul_f32_e32 v80, v80, v81
	v_mul_f32_e32 v81, v79, v82
	v_exp_f32_e32 v66, v66
	v_mul_f32_e32 v69, v130, v69
	v_fmac_f32_e32 v81, v75, v139
	v_mul_f32_e32 v73, v73, v96
	v_fma_f32 v96, -v71, v71, 1.0
	v_add_f32_e32 v65, v128, v65
	v_exp_f32_e32 v69, v69
	v_mul_f32_e32 v75, v79, v80
	v_mul_f32_e32 v79, v78, v81
	v_add_f32_e32 v67, 1.0, v67
	v_max_f32_e32 v96, 0, v96
	v_exp_f32_e32 v65, v65
	v_mul_f32_e32 v68, v130, v68
	v_fmac_f32_e32 v79, v74, v138
	v_mul_f32_e32 v72, v72, v97
	v_rcp_f32_e32 v67, v67
	v_sqrt_f32_e32 v96, v96
	v_fma_f32 v97, -v70, v70, 1.0
	v_add_f32_e32 v64, v128, v64
	v_exp_f32_e32 v68, v68
	v_mul_f32_e32 v74, v78, v75
	v_mul_f32_e32 v75, v77, v79
	v_add_f32_e32 v66, 1.0, v66
	v_max_f32_e32 v97, 0, v97
	v_exp_f32_e32 v64, v64
	v_fmac_f32_e32 v75, v73, v137
	v_rcp_f32_e32 v66, v66
	v_sqrt_f32_e32 v97, v97
	v_fma_f32 v98, -v69, v69, 1.0
	v_mul_f32_e32 v73, v77, v74
	v_mul_f32_e32 v74, v76, v75
	v_add_f32_e32 v65, 1.0, v65
	v_max_f32_e32 v98, 0, v98
	v_fmac_f32_e32 v74, v72, v136
	v_rcp_f32_e32 v65, v65
	v_sqrt_f32_e32 v98, v98
	v_fma_f32 v99, -v68, v68, 1.0
	v_mul_f32_e32 v67, v67, v96
	v_mul_f32_e32 v72, v76, v73
	v_mul_f32_e32 v73, v71, v74
	v_add_f32_e32 v64, 1.0, v64
	v_max_f32_e32 v99, 0, v99
	v_fmac_f32_e32 v73, v67, v135
	v_rcp_f32_e32 v64, v64
	v_sqrt_f32_e32 v99, v99
	v_mul_f32_e32 v66, v66, v97
	v_mul_f32_e32 v67, v71, v72
	v_mul_f32_e32 v71, v70, v73
	v_fmac_f32_e32 v71, v66, v134
	v_mul_f32_e32 v65, v65, v98
	v_mul_f32_e32 v66, v70, v67
	v_mul_f32_e32 v67, v69, v71
	v_fmac_f32_e32 v67, v65, v133
	v_mul_f32_e32 v64, v64, v99
	v_mul_f32_e32 v65, v69, v66
	v_mul_f32_e32 v71, v68, v67
	v_fmac_f32_e32 v71, v64, v132
	v_mul_f32_e32 v67, v68, v65
	ds_bpermute_b32 v64, v162, v67
	ds_bpermute_b32 v66, v164, v67
	ds_bpermute_b32 v65, v165, v67
	ds_bpermute_b32 v67, v166, v67
	ds_bpermute_b32 v68, v162, v71
	ds_bpermute_b32 v69, v164, v71
	ds_bpermute_b32 v70, v165, v71
	ds_bpermute_b32 v71, v166, v71
	s_and_saveexec_b64 s[0:1], s[4:5]
	s_cbranch_execz .LBB0_1520
	s_waitcnt lgkmcnt(0)
	v_fmac_f32_e32 v71, 0, v67
	v_fmac_f32_e32 v70, v71, v65
	v_fmac_f32_e32 v69, v70, v66
	v_fmac_f32_e32 v68, v69, v64
	v_mul_f32_e64 v64, v64, v66
	v_mul_f32_e64 v65, v65, v67
	s_add_i32 s11, s10, s11
	v_mad_u64_u32 v[66:67], s[12:13], s11, v163, v[124:125]
	v_pk_mul_f32 v[64:65], v[64:65], v[64:65] op_sel:[0,1] op_sel_hi:[1,0]
	v_lshl_add_u64 v[66:67], v[66:67], 3, s[36:37]
	v_mov_b32_e32 v65, v68
	global_store_dwordx2 v[66:67], v[64:65], off
	s_branch .LBB0_1520

.LBB0_1674:
	s_add_i32 s15, s0, s12
	v_mad_i64_i32 v[64:65], s[16:17], s15, v197, v[178:179]
	s_addk_i32 s15, 0x210
	s_lshl_b32 s13, s0, 6
	global_load_dword v204, v[64:65], off
	v_mad_u64_u32 v[64:65], s[16:17], s15, v197, v[178:179]
	global_load_dword v203, v[64:65], off
	v_add_u32_e32 v202, s13, v198
	v_mov_b64_e32 v[64:65], s[36:37]
	v_mad_i64_i32 v[64:65], s[16:17], v202, s53, v[64:65]
	v_lshl_add_u64 v[64:65], s[76:77], 1, v[64:65]
	v_lshl_add_u64 v[64:65], v[64:65], 0, v[156:157]
	v_lshl_add_u64 v[66:67], v[64:65], 0, s[74:75]
	v_add_co_u32_e32 v64, vcc, s88, v64
	v_add_u32_e32 v72, s13, v161
	s_movk_i32 s13, 0x110
	v_addc_co_u32_e32 v65, vcc, 0, v65, vcc
	v_mad_u64_u32 v[72:73], s[16:17], v72, s13, v[160:161]
	global_load_dwordx4 v[68:71], v[64:65], off offset:2560
	s_nop 0
	global_load_dwordx4 v[64:67], v[66:67], off offset:16
	ds_read_b128 v[76:79], v171 offset:2048
	ds_read_b128 v[114:117], v171 offset:2064
	ds_read_b128 v[150:153], v171 offset:2080
	ds_read_b128 v[80:83], v171 offset:2096
	ds_read_b128 v[118:121], v72 offset:55296
	ds_read_b128 v[84:87], v72 offset:55312
	v_add_u32_e32 v73, v160, v158
	ds_read_b128 v[206:209], v73
	ds_read_b128 v[146:149], v73 offset:16
	ds_read_b128 v[210:213], v73 offset:32
	ds_read_b128 v[110:113], v73 offset:48
	ds_read_b128 v[130:133], v72 offset:55568
	ds_read_b128 v[98:101], v72 offset:55584
	ds_read_b128 v[214:217], v73 offset:512
	ds_read_b128 v[142:145], v73 offset:528
	ds_read_b128 v[218:221], v73 offset:544
	ds_read_b128 v[106:109], v73 offset:560
	ds_read_b128 v[126:129], v72 offset:55840
	ds_read_b128 v[94:97], v72 offset:55856
	ds_read_b128 v[222:225], v73 offset:1024
	ds_read_b128 v[138:141], v73 offset:1040
	ds_read_b128 v[226:229], v73 offset:1056
	ds_read_b128 v[102:105], v73 offset:1072
	ds_read_b128 v[122:125], v72 offset:56112
	ds_read_b128 v[90:93], v72 offset:56128
	ds_read_b128 v[230:233], v73 offset:1536
	ds_read_b128 v[134:137], v73 offset:1552
	ds_read_b128 v[234:237], v73 offset:1568
	ds_read_b128 v[72:75], v73 offset:1584
	s_add_i32 s0, s0, 1
	s_waitcnt lgkmcnt(14)
	v_lshlrev_b32_e32 v88, 16, v118
	v_and_b32_e32 v89, 0xffff0000, v118
	v_fma_f32 v76, v206, v88, v76
	v_fma_f32 v77, v207, v89, v77
	v_lshlrev_b32_e32 v88, 16, v130
	v_and_b32_e32 v89, 0xffff0000, v130
	v_fma_f32 v76, v214, v88, v76
	v_fma_f32 v77, v215, v89, v77
	s_waitcnt lgkmcnt(11)
	v_lshlrev_b32_e32 v88, 16, v126
	v_and_b32_e32 v89, 0xffff0000, v126
	s_waitcnt lgkmcnt(9)
	v_fma_f32 v76, v222, v88, v76
	v_fma_f32 v77, v223, v89, v77
	s_waitcnt lgkmcnt(5)
	v_lshlrev_b32_e32 v88, 16, v122
	v_and_b32_e32 v89, 0xffff0000, v122
	s_waitcnt lgkmcnt(3)
	v_fma_f32 v76, v230, v88, v76
	v_fma_f32 v77, v231, v89, v77
	v_lshlrev_b32_e32 v88, 16, v84
	v_and_b32_e32 v89, 0xffff0000, v84
	v_lshlrev_b32_e32 v84, 16, v85
	v_and_b32_e32 v85, 0xffff0000, v85
	v_fma_f32 v88, v210, v88, v150
	v_fma_f32 v89, v211, v89, v151
	v_lshlrev_b32_e32 v150, 16, v98
	v_and_b32_e32 v151, 0xffff0000, v98
	v_fma_f32 v84, v212, v84, v152
	v_fma_f32 v85, v213, v85, v153
	v_lshlrev_b32_e32 v98, 16, v99
	v_and_b32_e32 v99, 0xffff0000, v99
	v_fma_f32 v88, v218, v150, v88
	v_fma_f32 v89, v219, v151, v89
	v_lshlrev_b32_e32 v150, 16, v94
	v_and_b32_e32 v151, 0xffff0000, v94
	v_fma_f32 v84, v220, v98, v84
	v_fma_f32 v85, v221, v99, v85
	v_lshlrev_b32_e32 v94, 16, v95
	v_and_b32_e32 v95, 0xffff0000, v95
	v_fma_f32 v88, v226, v150, v88
	v_fma_f32 v89, v227, v151, v89
	v_lshlrev_b32_e32 v150, 16, v90
	v_and_b32_e32 v151, 0xffff0000, v90
	v_fma_f32 v84, v228, v94, v84
	v_fma_f32 v85, v229, v95, v85
	v_lshlrev_b32_e32 v90, 16, v91
	v_and_b32_e32 v91, 0xffff0000, v91
	s_waitcnt lgkmcnt(1)
	v_fma_f32 v90, v236, v90, v84
	v_fma_f32 v91, v237, v91, v85
	v_lshlrev_b32_e32 v84, 16, v120
	v_and_b32_e32 v85, 0xffff0000, v120
	v_fma_f32 v84, v146, v84, v114
	v_fma_f32 v85, v147, v85, v115
	v_lshlrev_b32_e32 v94, 16, v132
	v_and_b32_e32 v95, 0xffff0000, v132
	v_fma_f32 v84, v142, v94, v84
	v_fma_f32 v85, v143, v95, v85
	v_lshlrev_b32_e32 v94, 16, v128
	v_and_b32_e32 v95, 0xffff0000, v128
	v_fma_f32 v84, v138, v94, v84
	v_fma_f32 v85, v139, v95, v85
	v_lshlrev_b32_e32 v94, 16, v124
	v_and_b32_e32 v95, 0xffff0000, v124
	v_fma_f32 v114, v134, v94, v84
	v_fma_f32 v115, v135, v95, v85
	v_lshlrev_b32_e32 v84, 16, v86
	v_and_b32_e32 v85, 0xffff0000, v86
	v_fma_f32 v80, v110, v84, v80
	v_fma_f32 v81, v111, v85, v81
	v_lshlrev_b32_e32 v84, 16, v100
	v_and_b32_e32 v85, 0xffff0000, v100
	v_fma_f32 v80, v106, v84, v80
	v_fma_f32 v81, v107, v85, v81
	v_lshlrev_b32_e32 v84, 16, v96
	v_and_b32_e32 v85, 0xffff0000, v96
	v_fma_f32 v80, v102, v84, v80
	v_fma_f32 v81, v103, v85, v81
	v_lshlrev_b32_e32 v84, 16, v92
	v_and_b32_e32 v85, 0xffff0000, v92
	s_waitcnt lgkmcnt(0)
	v_fma_f32 v72, v72, v84, v80
	v_fma_f32 v73, v73, v85, v81
	v_lshlrev_b32_e32 v80, 16, v121
	v_and_b32_e32 v81, 0xffff0000, v121
	v_fma_f32 v80, v148, v80, v116
	v_fma_f32 v81, v149, v81, v117
	v_lshlrev_b32_e32 v84, 16, v133
	v_and_b32_e32 v85, 0xffff0000, v133
	v_fma_f32 v80, v144, v84, v80
	v_fma_f32 v81, v145, v85, v81
	v_lshlrev_b32_e32 v84, 16, v129
	v_and_b32_e32 v85, 0xffff0000, v129
	v_lshlrev_b32_e32 v118, 16, v119
	v_and_b32_e32 v119, 0xffff0000, v119
	v_fma_f32 v80, v140, v84, v80
	v_fma_f32 v81, v141, v85, v81
	v_lshlrev_b32_e32 v84, 16, v125
	v_and_b32_e32 v85, 0xffff0000, v125
	v_fma_f32 v78, v208, v118, v78
	v_fma_f32 v79, v209, v119, v79
	v_lshlrev_b32_e32 v118, 16, v131
	v_and_b32_e32 v119, 0xffff0000, v131
	v_fma_f32 v116, v136, v84, v80
	v_fma_f32 v117, v137, v85, v81
	v_lshlrev_b32_e32 v80, 16, v87
	v_and_b32_e32 v81, 0xffff0000, v87
	v_fma_f32 v78, v216, v118, v78
	v_fma_f32 v79, v217, v119, v79
	v_lshlrev_b32_e32 v118, 16, v127
	v_and_b32_e32 v119, 0xffff0000, v127
	v_fma_f32 v80, v112, v80, v82
	v_fma_f32 v81, v113, v81, v83
	v_lshlrev_b32_e32 v82, 16, v101
	v_and_b32_e32 v83, 0xffff0000, v101
	v_fma_f32 v78, v224, v118, v78
	v_fma_f32 v79, v225, v119, v79
	v_lshlrev_b32_e32 v118, 16, v123
	v_and_b32_e32 v119, 0xffff0000, v123
	v_fma_f32 v80, v108, v82, v80
	v_fma_f32 v81, v109, v83, v81
	v_lshlrev_b32_e32 v82, 16, v97
	v_and_b32_e32 v83, 0xffff0000, v97
	v_fma_f32 v78, v232, v118, v78
	v_fma_f32 v79, v233, v119, v79
	v_fma_f32 v80, v104, v82, v80
	v_fma_f32 v81, v105, v83, v81
	v_lshlrev_b32_e32 v82, 16, v93
	v_and_b32_e32 v83, 0xffff0000, v93
	v_fma_f32 v88, v234, v150, v88
	v_fma_f32 v89, v235, v151, v89
	v_fma_f32 v74, v74, v82, v80
	v_fma_f32 v75, v75, v83, v81
	ds_write_b128 v184, v[76:79] offset:4096
	ds_write_b128 v184, v[114:117] offset:4112
	ds_write_b128 v184, v[88:91] offset:4128
	ds_write_b128 v184, v[72:75] offset:4144
	v_cvt_pk_bf16_f32 v76, v76, v77
	v_cvt_pk_bf16_f32 v77, v78, v79
	v_cvt_pk_bf16_f32 v78, v114, v115
	v_cvt_pk_bf16_f32 v79, v116, v117
	v_cvt_pk_bf16_f32 v80, v88, v89
	v_cvt_pk_bf16_f32 v81, v90, v91
	v_cvt_pk_bf16_f32 v82, v72, v73
	v_cvt_pk_bf16_f32 v83, v74, v75
	ds_write_b128 v185, v[76:79] offset:37888
	ds_write_b128 v185, v[80:83] offset:37904
	s_waitcnt lgkmcnt(0)
	s_barrier
	ds_read_b128 v[72:75], v192 offset:37888
	ds_read_b128 v[136:139], v192 offset:37952
	s_waitcnt lgkmcnt(1)
	v_mfma_f32_16x16x32_bf16 v[76:79], v[72:75], v[0:3], 0
	ds_read_b128 v[88:91], v192 offset:42240
	ds_read_b128 v[104:107], v192 offset:46592
	ds_read_b128 v[120:123], v192 offset:50944
	v_mfma_f32_16x16x32_bf16 v[80:83], v[72:75], v[20:23], 0
	s_cmp_ge_i32 s0, s1
	v_mfma_f32_16x16x32_bf16 v[84:87], v[72:75], v[36:39], 0
	s_waitcnt vmcnt(5)
	v_mfma_f32_16x16x32_bf16 v[72:75], v[72:75], v[56:59], 0
	s_waitcnt lgkmcnt(3)
	v_mfma_f32_16x16x32_bf16 v[76:79], v[136:139], v[4:7], v[76:79]
	v_mfma_f32_16x16x32_bf16 v[80:83], v[136:139], v[16:19], v[80:83]
	v_mfma_f32_16x16x32_bf16 v[84:87], v[136:139], v[32:35], v[84:87]
	v_mfma_f32_16x16x32_bf16 v[72:75], v[136:139], v[48:51], v[72:75]
	ds_read_b128 v[136:139], v192 offset:42304
	s_waitcnt lgkmcnt(3)
	v_mfma_f32_16x16x32_bf16 v[92:95], v[88:91], v[0:3], 0
	v_mfma_f32_16x16x32_bf16 v[96:99], v[88:91], v[20:23], 0
	v_mfma_f32_16x16x32_bf16 v[100:103], v[88:91], v[36:39], 0
	v_mfma_f32_16x16x32_bf16 v[88:91], v[88:91], v[56:59], 0
	s_waitcnt lgkmcnt(0)
	v_mfma_f32_16x16x32_bf16 v[92:95], v[136:139], v[4:7], v[92:95]
	v_mfma_f32_16x16x32_bf16 v[96:99], v[136:139], v[16:19], v[96:99]
	v_mfma_f32_16x16x32_bf16 v[100:103], v[136:139], v[32:35], v[100:103]
	v_mfma_f32_16x16x32_bf16 v[88:91], v[136:139], v[48:51], v[88:91]
	ds_read_b128 v[136:139], v192 offset:46656
	v_mfma_f32_16x16x32_bf16 v[108:111], v[104:107], v[0:3], 0
	v_mfma_f32_16x16x32_bf16 v[112:115], v[104:107], v[20:23], 0
	v_mfma_f32_16x16x32_bf16 v[116:119], v[104:107], v[36:39], 0
	v_mfma_f32_16x16x32_bf16 v[104:107], v[104:107], v[56:59], 0
	s_waitcnt lgkmcnt(0)
	v_mfma_f32_16x16x32_bf16 v[108:111], v[136:139], v[4:7], v[108:111]
	v_mfma_f32_16x16x32_bf16 v[112:115], v[136:139], v[16:19], v[112:115]
	v_mfma_f32_16x16x32_bf16 v[116:119], v[136:139], v[32:35], v[116:119]
	v_mfma_f32_16x16x32_bf16 v[104:107], v[136:139], v[48:51], v[104:107]
	ds_read_b128 v[136:139], v192 offset:51008
	v_mfma_f32_16x16x32_bf16 v[124:127], v[120:123], v[0:3], 0
	v_mfma_f32_16x16x32_bf16 v[128:131], v[120:123], v[20:23], 0
	v_mfma_f32_16x16x32_bf16 v[132:135], v[120:123], v[36:39], 0
	v_mfma_f32_16x16x32_bf16 v[120:123], v[120:123], v[56:59], 0
	s_waitcnt lgkmcnt(0)
	v_mfma_f32_16x16x32_bf16 v[124:127], v[136:139], v[4:7], v[124:127]
	v_mfma_f32_16x16x32_bf16 v[128:131], v[136:139], v[16:19], v[128:131]
	v_mfma_f32_16x16x32_bf16 v[132:135], v[136:139], v[32:35], v[132:135]
	v_mfma_f32_16x16x32_bf16 v[120:123], v[136:139], v[48:51], v[120:123]
	ds_read_b128 v[136:139], v192 offset:38016
	s_waitcnt lgkmcnt(0)
	v_mfma_f32_16x16x32_bf16 v[76:79], v[136:139], v[8:11], v[76:79]
	v_mfma_f32_16x16x32_bf16 v[80:83], v[136:139], v[24:27], v[80:83]
	v_mfma_f32_16x16x32_bf16 v[84:87], v[136:139], v[40:43], v[84:87]
	v_mfma_f32_16x16x32_bf16 v[136:139], v[136:139], v[52:55], v[72:75]
	s_nop 2
	ds_read_b128 v[72:75], v192 offset:42368
	s_waitcnt lgkmcnt(0)
	v_mfma_f32_16x16x32_bf16 v[92:95], v[72:75], v[8:11], v[92:95]
	v_mfma_f32_16x16x32_bf16 v[96:99], v[72:75], v[24:27], v[96:99]
	v_mfma_f32_16x16x32_bf16 v[100:103], v[72:75], v[40:43], v[100:103]
	v_mfma_f32_16x16x32_bf16 v[88:91], v[72:75], v[52:55], v[88:91]
	ds_read_b128 v[72:75], v192 offset:46720
	s_waitcnt lgkmcnt(0)
	v_mfma_f32_16x16x32_bf16 v[140:143], v[72:75], v[8:11], v[108:111]
	v_mfma_f32_16x16x32_bf16 v[144:147], v[72:75], v[24:27], v[112:115]
	v_mfma_f32_16x16x32_bf16 v[148:151], v[72:75], v[40:43], v[116:119]
	s_nop 1
	ds_read_b128 v[112:115], v192 offset:38080
	v_mfma_f32_16x16x32_bf16 v[206:209], v[72:75], v[52:55], v[104:107]
	ds_read_b128 v[72:75], v192 offset:51072
	s_waitcnt lgkmcnt(0)
	v_mfma_f32_16x16x32_bf16 v[210:213], v[72:75], v[8:11], v[124:127]
	v_mfma_f32_16x16x32_bf16 v[128:131], v[72:75], v[24:27], v[128:131]
	v_mfma_f32_16x16x32_bf16 v[132:135], v[72:75], v[40:43], v[132:135]
	v_mfma_f32_16x16x32_bf16 v[214:217], v[72:75], v[52:55], v[120:123]
	v_mfma_f32_16x16x32_bf16 v[72:75], v[112:115], v[44:47], v[84:87]
	s_nop 2
	ds_read_b128 v[84:87], v192 offset:42432
	v_mfma_f32_16x16x32_bf16 v[104:107], v[112:115], v[12:15], v[76:79]
	s_nop 2
	v_add_f32_e32 v75, v173, v75
	v_exp_f32_e32 v75, v75
	v_add_f32_e32 v74, v173, v74
	v_mfma_f32_16x16x32_bf16 v[108:111], v[112:115], v[28:31], v[80:83]
	v_exp_f32_e32 v74, v74
	v_add_f32_e32 v107, v172, v107
	v_exp_f32_e32 v107, v107
	s_waitcnt vmcnt(4)
	v_mfma_f32_16x16x32_bf16 v[76:79], v[112:115], v[60:63], v[136:139]
	v_add_f32_e32 v106, v172, v106
	v_exp_f32_e32 v106, v106
	v_add_f32_e32 v107, 1.0, v107
	s_waitcnt lgkmcnt(0)
	v_mfma_f32_16x16x32_bf16 v[112:115], v[84:87], v[12:15], v[92:95]
	v_rcp_f32_e32 v107, v107
	v_add_f32_e32 v111, v174, v111
	v_add_f32_e32 v106, 1.0, v106
	v_mfma_f32_16x16x32_bf16 v[80:83], v[84:87], v[44:47], v[100:103]
	ds_read_b128 v[92:95], v192 offset:46784
	s_nop 2
	v_add_f32_e32 v115, v172, v115
	v_exp_f32_e32 v115, v115
	ds_read_b128 v[100:103], v192 offset:51136
	v_mfma_f32_16x16x32_bf16 v[116:119], v[84:87], v[28:31], v[96:99]
	v_add_f32_e32 v114, v172, v114
	v_add_f32_e32 v115, 1.0, v115
	v_rcp_f32_e32 v115, v115
	v_mfma_f32_16x16x32_bf16 v[84:87], v[84:87], v[60:63], v[88:91]
	v_exp_f32_e32 v114, v114
	s_nop 2
	v_add_f32_e32 v119, v174, v119
	v_mul_f32_e32 v115, v176, v115
	s_waitcnt lgkmcnt(1)
	v_mfma_f32_16x16x32_bf16 v[88:91], v[92:95], v[44:47], v[148:151]
	v_exp_f32_e32 v115, v115
	v_add_f32_e32 v114, 1.0, v114
	v_exp_f32_e32 v119, v119
	s_waitcnt lgkmcnt(0)
	v_mfma_f32_16x16x32_bf16 v[148:151], v[100:103], v[12:15], v[210:213]
	v_rcp_f32_e32 v114, v114
	v_add_f32_e32 v113, v172, v113
	v_exp_f32_e32 v113, v113
	v_mfma_f32_16x16x32_bf16 v[124:127], v[92:95], v[28:31], v[144:147]
	v_add_f32_e32 v119, 1.0, v119
	s_nop 2
	v_add_f32_e32 v148, v172, v148
	v_exp_f32_e32 v148, v148
	v_add_f32_e32 v145, v172, v151
	v_exp_f32_e32 v145, v145
	v_mfma_f32_16x16x32_bf16 v[120:123], v[92:95], v[12:15], v[140:143]
	v_add_f32_e32 v146, v172, v150
	v_exp_f32_e32 v146, v146
	v_add_f32_e32 v145, 1.0, v145
	v_rcp_f32_e32 v145, v145
	v_mfma_f32_16x16x32_bf16 v[92:95], v[92:95], v[60:63], v[206:209]
	v_add_f32_e32 v146, 1.0, v146
	v_rcp_f32_e32 v146, v146
	v_mul_f32_e32 v145, v176, v145
	v_mfma_f32_16x16x32_bf16 v[206:209], v[100:103], v[28:31], v[128:131]
	v_exp_f32_e32 v151, v145
	v_mul_f32_e32 v146, v176, v146
	v_add_f32_e32 v147, v172, v149
	v_exp_f32_e32 v150, v146
	v_fma_f32 v145, -v151, v151, 1.0
	s_nop 2
	v_add_f32_e32 v144, v174, v209
	v_exp_f32_e32 v144, v144
	v_max_f32_e32 v145, 0, v145
	v_sqrt_f32_e32 v145, v145
	v_exp_f32_e32 v147, v147
	v_add_f32_e32 v144, 1.0, v144
	v_rcp_f32_e32 v144, v144
	v_fma_f32 v146, -v150, v150, 1.0
	v_add_f32_e32 v147, 1.0, v147
	v_max_f32_e32 v146, 0, v146
	v_mul_f32_e32 v144, v144, v145
	v_add_f32_e32 v145, v174, v208
	v_exp_f32_e32 v145, v145
	v_rcp_f32_e32 v147, v147
	v_sqrt_f32_e32 v146, v146
	v_add_f32_e32 v148, 1.0, v148
	v_add_f32_e32 v145, 1.0, v145
	v_rcp_f32_e32 v145, v145
	v_mul_f32_e32 v147, v176, v147
	v_exp_f32_e32 v149, v147
	v_rcp_f32_e32 v148, v148
	v_mul_f32_e32 v145, v145, v146
	v_add_f32_e32 v146, v174, v207
	v_exp_f32_e32 v146, v146
	v_fma_f32 v147, -v149, v149, 1.0
	v_max_f32_e32 v147, 0, v147
	v_sqrt_f32_e32 v147, v147
	v_add_f32_e32 v146, 1.0, v146
	v_rcp_f32_e32 v146, v146
	v_mul_f32_e32 v148, v176, v148
	v_add_f32_e32 v123, v172, v123
	v_exp_f32_e32 v148, v148
	v_mul_f32_e32 v146, v146, v147
	v_add_f32_e32 v147, v174, v206
	v_exp_f32_e32 v123, v123
	v_exp_f32_e32 v147, v147
	v_fma_f32 v152, -v148, v148, 1.0
	v_max_f32_e32 v152, 0, v152
	v_add_f32_e32 v123, 1.0, v123
	v_add_f32_e32 v147, 1.0, v147
	v_rcp_f32_e32 v123, v123
	v_rcp_f32_e32 v147, v147
	v_sqrt_f32_e32 v152, v152
	v_add_f32_e32 v122, v172, v122
	v_mul_f32_e32 v123, v176, v123
	v_add_f32_e32 v127, v174, v127
	v_mul_f32_e32 v147, v147, v152
	v_exp_f32_e32 v152, v123
	v_exp_f32_e32 v122, v122
	v_exp_f32_e32 v127, v127
	v_add_f32_e32 v121, v172, v121
	v_fma_f32 v123, -v152, v152, 1.0
	v_add_f32_e32 v122, 1.0, v122
	v_add_f32_e32 v127, 1.0, v127
	v_max_f32_e32 v123, 0, v123
	v_rcp_f32_e32 v122, v122
	v_rcp_f32_e32 v127, v127
	v_sqrt_f32_e32 v123, v123
	v_exp_f32_e32 v121, v121
	v_mul_f32_e32 v122, v176, v122
	v_add_f32_e32 v126, v174, v126
	v_mul_f32_e32 v123, v127, v123
	v_exp_f32_e32 v127, v122
	v_add_f32_e32 v121, 1.0, v121
	v_exp_f32_e32 v126, v126
	v_rcp_f32_e32 v121, v121
	v_add_f32_e32 v120, v172, v120
	v_exp_f32_e32 v120, v120
	v_fma_f32 v122, -v127, v127, 1.0
	v_add_f32_e32 v126, 1.0, v126
	v_max_f32_e32 v122, 0, v122
	v_mul_f32_e32 v121, v176, v121
	v_rcp_f32_e32 v126, v126
	v_sqrt_f32_e32 v122, v122
	v_add_f32_e32 v125, v174, v125
	v_exp_f32_e32 v121, v121
	v_add_f32_e32 v120, 1.0, v120
	v_exp_f32_e32 v125, v125
	v_rcp_f32_e32 v120, v120
	v_mul_f32_e32 v122, v126, v122
	v_fma_f32 v126, -v121, v121, 1.0
	v_add_f32_e32 v125, 1.0, v125
	v_max_f32_e32 v126, 0, v126
	v_mul_f32_e32 v120, v176, v120
	v_rcp_f32_e32 v125, v125
	v_sqrt_f32_e32 v126, v126
	v_add_f32_e32 v124, v174, v124
	v_exp_f32_e32 v120, v120
	v_exp_f32_e32 v124, v124
	v_mul_f32_e32 v125, v125, v126
	v_mul_f32_e32 v114, v176, v114
	v_fma_f32 v126, -v120, v120, 1.0
	v_add_f32_e32 v124, 1.0, v124
	v_max_f32_e32 v126, 0, v126
	v_rcp_f32_e32 v124, v124
	v_sqrt_f32_e32 v126, v126
	v_rcp_f32_e32 v119, v119
	v_add_f32_e32 v118, v174, v118
	v_exp_f32_e32 v114, v114
	v_mul_f32_e32 v124, v124, v126
	v_fma_f32 v126, -v115, v115, 1.0
	v_max_f32_e32 v126, 0, v126
	v_sqrt_f32_e32 v126, v126
	v_add_f32_e32 v113, 1.0, v113
	v_exp_f32_e32 v118, v118
	v_rcp_f32_e32 v113, v113
	v_add_f32_e32 v112, v172, v112
	v_exp_f32_e32 v112, v112
	v_mul_f32_e32 v119, v119, v126
	v_fma_f32 v126, -v114, v114, 1.0
	v_add_f32_e32 v118, 1.0, v118
	v_max_f32_e32 v126, 0, v126
	v_mul_f32_e32 v113, v176, v113
	v_rcp_f32_e32 v118, v118
	v_sqrt_f32_e32 v126, v126
	v_add_f32_e32 v117, v174, v117
	v_exp_f32_e32 v113, v113
	v_add_f32_e32 v112, 1.0, v112
	v_exp_f32_e32 v117, v117
	v_rcp_f32_e32 v112, v112
	v_mul_f32_e32 v118, v118, v126
	v_fma_f32 v126, -v113, v113, 1.0
	v_add_f32_e32 v117, 1.0, v117
	v_max_f32_e32 v126, 0, v126
	v_mul_f32_e32 v112, v176, v112
	v_rcp_f32_e32 v117, v117
	v_sqrt_f32_e32 v126, v126
	v_add_f32_e32 v116, v174, v116
	v_exp_f32_e32 v112, v112
	v_exp_f32_e32 v116, v116
	v_mul_f32_e32 v117, v117, v126
	v_mul_f32_e32 v107, v176, v107
	v_fma_f32 v126, -v112, v112, 1.0
	v_add_f32_e32 v116, 1.0, v116
	v_max_f32_e32 v126, 0, v126
	v_rcp_f32_e32 v116, v116
	v_sqrt_f32_e32 v126, v126
	v_exp_f32_e32 v107, v107
	v_exp_f32_e32 v111, v111
	v_rcp_f32_e32 v106, v106
	v_add_f32_e32 v105, v172, v105
	v_exp_f32_e32 v105, v105
	v_mul_f32_e32 v116, v116, v126
	v_fma_f32 v126, -v107, v107, 1.0
	v_add_f32_e32 v111, 1.0, v111
	v_max_f32_e32 v126, 0, v126
	v_mul_f32_e32 v106, v176, v106
	v_rcp_f32_e32 v111, v111
	v_sqrt_f32_e32 v126, v126
	v_add_f32_e32 v110, v174, v110
	v_exp_f32_e32 v106, v106
	v_add_f32_e32 v105, 1.0, v105
	v_exp_f32_e32 v110, v110
	v_rcp_f32_e32 v105, v105
	v_add_f32_e32 v104, v172, v104
	v_exp_f32_e32 v104, v104
	v_mul_f32_e32 v111, v111, v126
	v_fma_f32 v126, -v106, v106, 1.0
	v_add_f32_e32 v110, 1.0, v110
	v_max_f32_e32 v126, 0, v126
	v_mul_f32_e32 v105, v176, v105
	v_rcp_f32_e32 v110, v110
	v_sqrt_f32_e32 v126, v126
	v_add_f32_e32 v109, v174, v109
	v_exp_f32_e32 v105, v105
	v_add_f32_e32 v104, 1.0, v104
	v_exp_f32_e32 v109, v109
	v_rcp_f32_e32 v104, v104
	v_mul_f32_e32 v110, v110, v126
	v_fma_f32 v126, -v105, v105, 1.0
	v_add_f32_e32 v109, 1.0, v109
	v_max_f32_e32 v126, 0, v126
	v_mul_f32_e32 v104, v176, v104
	v_rcp_f32_e32 v109, v109
	v_sqrt_f32_e32 v126, v126
	v_add_f32_e32 v108, v174, v108
	v_exp_f32_e32 v104, v104
	v_exp_f32_e32 v108, v108
	v_mul_f32_e32 v109, v109, v126
	v_add_u32_e32 v128, 0x1000, v193
	v_fma_f32 v126, -v104, v104, 1.0
	v_add_f32_e32 v108, 1.0, v108
	v_max_f32_e32 v126, 0, v126
	ds_read2_b32 v[128:129], v128 offset1:132
	v_rcp_f32_e32 v108, v108
	v_sqrt_f32_e32 v126, v126
	v_add_u32_e32 v130, 0x1400, v193
	ds_read2_b32 v[130:131], v130 offset0:8 offset1:140
	v_mfma_f32_16x16x32_bf16 v[96:99], v[100:103], v[44:47], v[132:135]
	v_mul_f32_e32 v108, v108, v126
	s_waitcnt lgkmcnt(1)
	v_mul_f32_e32 v108, v108, v128
	v_mul_f32_e32 v109, v109, v129
	v_add_u32_e32 v132, 0x3000, v193
	ds_read2_b32 v[132:133], v132 offset0:64 offset1:196
	v_add_u32_e32 v134, 0x3400, v193
	ds_read2_b32 v[134:135], v134 offset0:72 offset1:204
	v_fma_f32 v126, 0, v104, v108
	v_add_u32_e32 v136, 0x5200, v193
	s_waitcnt lgkmcnt(2)
	v_mul_f32_e32 v110, v110, v130
	v_fma_f32 v126, v105, v126, v109
	v_mul_f32_e32 v153, v104, v105
	ds_read2_b32 v[136:137], v136 offset1:132
	v_mul_f32_e32 v111, v111, v131
	v_fma_f32 v126, v106, v126, v110
	v_mul_f32_e32 v153, v106, v153
	v_add_u32_e32 v138, 0x5600, v193
	s_waitcnt lgkmcnt(2)
	v_mul_f32_e32 v116, v116, v132
	v_fma_f32 v126, v107, v126, v111
	v_mul_f32_e32 v153, v107, v153
	ds_read2_b32 v[138:139], v138 offset0:8 offset1:140
	v_mul_f32_e32 v117, v117, v133
	v_fma_f32 v126, v112, v126, v116
	v_mul_f32_e32 v153, v153, v112
	v_add_u32_e32 v140, 0x7200, v193
	s_waitcnt lgkmcnt(2)
	v_mul_f32_e32 v118, v118, v134
	v_fma_f32 v126, v113, v126, v117
	v_mul_f32_e32 v153, v113, v153
	ds_read2_b32 v[140:141], v140 offset0:64 offset1:196
	v_mul_f32_e32 v119, v119, v135
	v_fma_f32 v126, v114, v126, v118
	v_mul_f32_e32 v153, v114, v153
	v_add_u32_e32 v142, 0x7600, v193
	s_waitcnt lgkmcnt(2)
	v_mul_f32_e32 v124, v124, v136
	v_fma_f32 v126, v115, v126, v119
	v_mul_f32_e32 v153, v115, v153
	ds_read2_b32 v[142:143], v142 offset0:72 offset1:204
	v_mul_f32_e32 v125, v125, v137
	v_fma_f32 v126, v120, v126, v124
	v_mul_f32_e32 v153, v153, v120
	s_waitcnt lgkmcnt(2)
	v_mul_f32_e32 v122, v122, v138
	v_fma_f32 v126, v121, v126, v125
	v_mul_f32_e32 v153, v121, v153
	v_mul_f32_e32 v123, v123, v139
	v_fma_f32 v126, v127, v126, v122
	v_mul_f32_e32 v153, v127, v153
	v_add_f32_e32 v99, v173, v99
	s_waitcnt lgkmcnt(1)
	v_mul_f32_e32 v147, v147, v140
	v_fma_f32 v126, v152, v126, v123
	v_mul_f32_e32 v153, v152, v153
	v_exp_f32_e32 v99, v99
	v_mul_f32_e32 v146, v146, v141
	v_fma_f32 v126, v148, v126, v147
	v_mul_f32_e32 v153, v153, v148
	s_waitcnt lgkmcnt(0)
	v_mul_f32_e32 v145, v145, v142
	v_fma_f32 v126, v149, v126, v146
	v_mul_f32_e32 v153, v149, v153
	v_mul_f32_e32 v144, v144, v143
	v_fma_f32 v126, v150, v126, v145
	v_mul_f32_e32 v153, v150, v153
	v_fma_f32 v126, v151, v126, v144
	v_mul_f32_e32 v153, v151, v153
	v_add_f32_e32 v99, 1.0, v99
	ds_bpermute_b32 v205, v196, v153
	ds_bpermute_b32 v207, v196, v126
	v_rcp_f32_e32 v99, v99
	v_add_f32_e32 v98, v173, v98
	v_mfma_f32_16x16x32_bf16 v[100:103], v[100:103], v[60:63], v[214:217]
	ds_bpermute_b32 v206, v199, v153
	ds_bpermute_b32 v208, v199, v126
	v_exp_f32_e32 v98, v98
	ds_bpermute_b32 v153, v200, v153
	ds_bpermute_b32 v126, v200, v126
	v_mul_f32_e32 v99, v177, v99
	s_waitcnt vmcnt(3) lgkmcnt(4)
	v_fmac_f32_e32 v207, v204, v205
	v_add_f32_e32 v103, v175, v103
	v_exp_f32_e32 v99, v99
	v_add_f32_e32 v98, 1.0, v98
	v_cndmask_b32_e64 v204, v204, v207, s[6:7]
	s_waitcnt lgkmcnt(2)
	v_fmac_f32_e32 v208, v207, v206
	v_exp_f32_e32 v103, v103
	v_rcp_f32_e32 v98, v98
	v_add_f32_e32 v97, v173, v97
	v_cndmask_b32_e64 v204, v204, v208, s[4:5]
	s_waitcnt lgkmcnt(0)
	v_fmac_f32_e32 v126, v208, v153
	v_exp_f32_e32 v97, v97
	v_cndmask_b32_e64 v126, v204, v126, s[10:11]
	v_fmac_f32_e32 v108, v104, v126
	v_fma_f32 v104, -v99, v99, 1.0
	v_add_f32_e32 v103, 1.0, v103
	v_max_f32_e32 v104, 0, v104
	v_mul_f32_e32 v98, v177, v98
	v_rcp_f32_e32 v103, v103
	v_sqrt_f32_e32 v104, v104
	v_add_f32_e32 v102, v175, v102
	v_exp_f32_e32 v98, v98
	v_add_f32_e32 v97, 1.0, v97
	v_exp_f32_e32 v102, v102
	v_rcp_f32_e32 v97, v97
	v_add_f32_e32 v96, v173, v96
	v_exp_f32_e32 v96, v96
	v_mul_f32_e32 v103, v103, v104
	v_fma_f32 v104, -v98, v98, 1.0
	v_add_f32_e32 v102, 1.0, v102
	v_max_f32_e32 v104, 0, v104
	v_mul_f32_e32 v97, v177, v97
	v_rcp_f32_e32 v102, v102
	v_sqrt_f32_e32 v104, v104
	v_add_f32_e32 v101, v175, v101
	v_exp_f32_e32 v97, v97
	v_add_f32_e32 v96, 1.0, v96
	v_exp_f32_e32 v101, v101
	v_rcp_f32_e32 v96, v96
	v_add_f32_e32 v91, v173, v91
	v_exp_f32_e32 v91, v91
	v_mul_f32_e32 v102, v102, v104
	v_fma_f32 v104, -v97, v97, 1.0
	v_add_f32_e32 v101, 1.0, v101
	v_max_f32_e32 v104, 0, v104
	v_mul_f32_e32 v96, v177, v96
	v_rcp_f32_e32 v101, v101
	v_sqrt_f32_e32 v104, v104
	v_add_f32_e32 v100, v175, v100
	v_exp_f32_e32 v96, v96
	v_add_f32_e32 v91, 1.0, v91
	v_exp_f32_e32 v100, v100
	v_rcp_f32_e32 v91, v91
	v_add_f32_e32 v90, v173, v90
	v_exp_f32_e32 v90, v90
	v_mul_f32_e32 v101, v101, v104
	v_fma_f32 v104, -v96, v96, 1.0
	v_add_f32_e32 v100, 1.0, v100
	v_max_f32_e32 v104, 0, v104
	v_mul_f32_e32 v91, v177, v91
	v_rcp_f32_e32 v100, v100
	v_sqrt_f32_e32 v104, v104
	v_add_f32_e32 v95, v175, v95
	v_exp_f32_e32 v91, v91
	v_add_f32_e32 v90, 1.0, v90
	v_exp_f32_e32 v95, v95
	v_rcp_f32_e32 v90, v90
	v_add_f32_e32 v89, v173, v89
	v_exp_f32_e32 v89, v89
	v_mul_f32_e32 v100, v100, v104
	v_fma_f32 v104, -v91, v91, 1.0
	v_add_f32_e32 v95, 1.0, v95
	v_max_f32_e32 v104, 0, v104
	v_mul_f32_e32 v90, v177, v90
	v_rcp_f32_e32 v95, v95
	v_sqrt_f32_e32 v104, v104
	v_add_f32_e32 v94, v175, v94
	v_exp_f32_e32 v90, v90
	v_add_f32_e32 v89, 1.0, v89
	v_exp_f32_e32 v94, v94
	v_rcp_f32_e32 v89, v89
	v_add_f32_e32 v88, v173, v88
	v_exp_f32_e32 v88, v88
	v_mul_f32_e32 v95, v95, v104
	v_fma_f32 v104, -v90, v90, 1.0
	v_add_f32_e32 v94, 1.0, v94
	v_max_f32_e32 v104, 0, v104
	v_mul_f32_e32 v89, v177, v89
	v_rcp_f32_e32 v94, v94
	v_sqrt_f32_e32 v104, v104
	v_add_f32_e32 v93, v175, v93
	v_exp_f32_e32 v89, v89
	v_add_f32_e32 v88, 1.0, v88
	v_exp_f32_e32 v93, v93
	v_rcp_f32_e32 v88, v88
	v_add_f32_e32 v83, v173, v83
	v_exp_f32_e32 v83, v83
	v_mul_f32_e32 v94, v94, v104
	v_fma_f32 v104, -v89, v89, 1.0
	v_add_f32_e32 v93, 1.0, v93
	v_max_f32_e32 v104, 0, v104
	v_mul_f32_e32 v88, v177, v88
	v_rcp_f32_e32 v93, v93
	v_sqrt_f32_e32 v104, v104
	v_add_f32_e32 v92, v175, v92
	v_exp_f32_e32 v88, v88
	v_add_f32_e32 v83, 1.0, v83
	v_exp_f32_e32 v92, v92
	v_rcp_f32_e32 v83, v83
	v_add_f32_e32 v82, v173, v82
	v_exp_f32_e32 v82, v82
	v_mul_f32_e32 v93, v93, v104
	v_fma_f32 v104, -v88, v88, 1.0
	v_add_f32_e32 v92, 1.0, v92
	v_max_f32_e32 v104, 0, v104
	v_mul_f32_e32 v83, v177, v83
	v_rcp_f32_e32 v92, v92
	v_sqrt_f32_e32 v104, v104
	v_add_f32_e32 v87, v175, v87
	v_exp_f32_e32 v83, v83
	v_add_f32_e32 v82, 1.0, v82
	v_exp_f32_e32 v87, v87
	v_rcp_f32_e32 v82, v82
	v_add_f32_e32 v81, v173, v81
	v_exp_f32_e32 v81, v81
	v_mul_f32_e32 v92, v92, v104
	v_fma_f32 v104, -v83, v83, 1.0
	v_add_f32_e32 v87, 1.0, v87
	v_max_f32_e32 v104, 0, v104
	v_mul_f32_e32 v82, v177, v82
	v_rcp_f32_e32 v87, v87
	v_sqrt_f32_e32 v104, v104
	v_add_f32_e32 v86, v175, v86
	v_exp_f32_e32 v82, v82
	v_add_f32_e32 v81, 1.0, v81
	v_exp_f32_e32 v86, v86
	v_rcp_f32_e32 v81, v81
	v_add_f32_e32 v80, v173, v80
	v_exp_f32_e32 v80, v80
	v_mul_f32_e32 v87, v87, v104
	v_fma_f32 v104, -v82, v82, 1.0
	v_add_f32_e32 v86, 1.0, v86
	v_max_f32_e32 v104, 0, v104
	v_mul_f32_e32 v81, v177, v81
	v_rcp_f32_e32 v86, v86
	v_sqrt_f32_e32 v104, v104
	v_add_f32_e32 v85, v175, v85
	v_exp_f32_e32 v81, v81
	v_exp_f32_e32 v85, v85
	v_add_f32_e32 v80, 1.0, v80
	v_rcp_f32_e32 v80, v80
	v_mul_f32_e32 v86, v86, v104
	v_fma_f32 v104, -v81, v81, 1.0
	v_add_f32_e32 v85, 1.0, v85
	v_max_f32_e32 v104, 0, v104
	v_rcp_f32_e32 v85, v85
	v_sqrt_f32_e32 v104, v104
	v_mul_f32_e32 v80, v177, v80
	v_add_f32_e32 v84, v175, v84
	v_exp_f32_e32 v80, v80
	v_exp_f32_e32 v84, v84
	v_add_f32_e32 v75, 1.0, v75
	v_rcp_f32_e32 v75, v75
	v_mul_f32_e32 v85, v85, v104
	v_mul_f32_e32 v104, v85, v133
	v_fma_f32 v85, -v80, v80, 1.0
	v_add_f32_e32 v84, 1.0, v84
	v_max_f32_e32 v85, 0, v85
	v_rcp_f32_e32 v84, v84
	v_sqrt_f32_e32 v85, v85
	v_mul_f32_e32 v75, v177, v75
	v_add_f32_e32 v79, v175, v79
	v_exp_f32_e32 v75, v75
	v_add_f32_e32 v74, 1.0, v74
	v_exp_f32_e32 v79, v79
	v_rcp_f32_e32 v74, v74
	v_add_f32_e32 v73, v173, v73
	v_exp_f32_e32 v73, v73
	v_mul_f32_e32 v84, v84, v85
	v_fmac_f32_e32 v109, v105, v108
	v_mul_f32_e32 v105, v84, v132
	v_fma_f32 v84, -v75, v75, 1.0
	v_add_f32_e32 v79, 1.0, v79
	v_max_f32_e32 v84, 0, v84
	v_mul_f32_e32 v74, v177, v74
	v_rcp_f32_e32 v79, v79
	v_sqrt_f32_e32 v84, v84
	v_add_f32_e32 v78, v175, v78
	v_exp_f32_e32 v74, v74
	v_add_f32_e32 v73, 1.0, v73
	v_exp_f32_e32 v78, v78
	v_rcp_f32_e32 v73, v73
	v_add_f32_e32 v72, v173, v72
	v_exp_f32_e32 v72, v72
	v_mul_f32_e32 v79, v79, v84
	v_fma_f32 v84, -v74, v74, 1.0
	v_add_f32_e32 v78, 1.0, v78
	v_max_f32_e32 v84, 0, v84
	v_mul_f32_e32 v73, v177, v73
	v_rcp_f32_e32 v78, v78
	v_sqrt_f32_e32 v84, v84
	v_add_f32_e32 v77, v175, v77
	v_exp_f32_e32 v73, v73
	v_add_f32_e32 v72, 1.0, v72
	v_exp_f32_e32 v77, v77
	v_rcp_f32_e32 v72, v72
	v_mul_f32_e32 v78, v78, v84
	v_fma_f32 v84, -v73, v73, 1.0
	v_add_f32_e32 v77, 1.0, v77
	v_max_f32_e32 v84, 0, v84
	v_mul_f32_e32 v72, v177, v72
	v_rcp_f32_e32 v77, v77
	v_sqrt_f32_e32 v84, v84
	v_add_f32_e32 v76, v175, v76
	v_exp_f32_e32 v72, v72
	v_exp_f32_e32 v76, v76
	v_mul_f32_e32 v77, v77, v84
	v_mul_f32_e32 v103, v103, v143
	v_fma_f32 v84, -v72, v72, 1.0
	v_add_f32_e32 v76, 1.0, v76
	v_max_f32_e32 v84, 0, v84
	v_rcp_f32_e32 v76, v76
	v_sqrt_f32_e32 v84, v84
	v_mul_f32_e32 v102, v102, v142
	v_mul_f32_e32 v101, v101, v141
	v_mul_f32_e32 v85, v99, v98
	v_mul_f32_e32 v76, v76, v84
	v_fma_f32 v84, 0, v99, v103
	v_fma_f32 v84, v98, v84, v102
	v_mul_f32_e32 v100, v100, v140
	v_fma_f32 v84, v97, v84, v101
	v_mul_f32_e32 v85, v97, v85
	v_mul_f32_e32 v95, v95, v139
	v_fma_f32 v84, v96, v84, v100
	v_mul_f32_e32 v85, v96, v85
	v_mul_f32_e32 v94, v94, v138
	v_fma_f32 v84, v91, v84, v95
	v_mul_f32_e32 v85, v91, v85
	v_mul_f32_e32 v93, v93, v137
	v_fma_f32 v84, v90, v84, v94
	v_mul_f32_e32 v85, v90, v85
	v_mul_f32_e32 v92, v92, v136
	v_fma_f32 v84, v89, v84, v93
	v_mul_f32_e32 v85, v89, v85
	v_mul_f32_e32 v87, v87, v135
	v_fma_f32 v84, v88, v84, v92
	v_mul_f32_e32 v85, v88, v85
	v_mul_f32_e32 v86, v86, v134
	v_fma_f32 v84, v83, v84, v87
	v_mul_f32_e32 v85, v83, v85
	v_fma_f32 v84, v82, v84, v86
	v_mul_f32_e32 v85, v82, v85
	v_fma_f32 v84, v81, v84, v104
	v_mul_f32_e32 v85, v81, v85
	v_mul_f32_e32 v79, v79, v131
	v_fma_f32 v84, v80, v84, v105
	v_mul_f32_e32 v85, v80, v85
	v_mul_f32_e32 v78, v78, v130
	v_fma_f32 v84, v75, v84, v79
	v_mul_f32_e32 v85, v75, v85
	v_fmac_f32_e32 v110, v106, v109
	v_mul_f32_e32 v77, v77, v129
	v_fma_f32 v84, v74, v84, v78
	v_mul_f32_e32 v85, v74, v85
	v_fmac_f32_e32 v111, v107, v110
	v_mul_f32_e32 v76, v76, v128
	v_fma_f32 v84, v73, v84, v77
	v_mul_f32_e32 v85, v73, v85
	v_fmac_f32_e32 v116, v112, v111
	v_fma_f32 v84, v72, v84, v76
	v_mul_f32_e32 v85, v72, v85
	v_fmac_f32_e32 v117, v113, v116
	ds_bpermute_b32 v106, v199, v85
	ds_bpermute_b32 v107, v200, v85
	ds_bpermute_b32 v85, v201, v85
	ds_bpermute_b32 v112, v199, v84
	ds_bpermute_b32 v113, v200, v84
	ds_bpermute_b32 v84, v201, v84
	v_fmac_f32_e32 v118, v114, v117
	v_fmac_f32_e32 v119, v115, v118
	v_fmac_f32_e32 v124, v120, v119
	v_fmac_f32_e32 v125, v121, v124
	s_waitcnt vmcnt(2) lgkmcnt(0)
	v_fmac_f32_e32 v84, v203, v85
	v_cndmask_b32_e64 v85, v203, v84, s[4:5]
	v_fmac_f32_e32 v113, v84, v107
	v_cndmask_b32_e64 v84, v85, v113, s[6:7]
	v_fmac_f32_e32 v112, v113, v106
	v_cndmask_b32_e64 v84, v84, v112, s[8:9]
	v_fmac_f32_e32 v103, v99, v84
	v_fmac_f32_e32 v102, v98, v103
	v_fmac_f32_e32 v101, v97, v102
	v_fmac_f32_e32 v100, v96, v101
	v_fmac_f32_e32 v95, v91, v100
	v_fmac_f32_e32 v94, v90, v95
	v_fmac_f32_e32 v93, v89, v94
	v_fmac_f32_e32 v92, v88, v93
	v_fmac_f32_e32 v87, v83, v92
	v_fmac_f32_e32 v86, v82, v87
	v_fmac_f32_e32 v104, v81, v86
	v_fmac_f32_e32 v105, v80, v104
	v_fmac_f32_e32 v79, v75, v105
	v_fmac_f32_e32 v78, v74, v79
	v_fmac_f32_e32 v77, v73, v78
	v_fmac_f32_e32 v76, v72, v77
	v_add_f32_e32 v88, v108, v76
	v_add_f32_e32 v89, v109, v77
	ds_write2_b32 v194, v88, v89 offset1:132
	s_waitcnt vmcnt(1)
	v_lshlrev_b32_e32 v88, 16, v68
	v_and_b32_e32 v89, 0xffff0000, v68
	v_mul_f32_e32 v68, 0xbfb8aa3b, v88
	v_exp_f32_e32 v68, v68
	v_fmac_f32_e32 v122, v127, v125
	v_add_f32_e32 v84, v110, v78
	v_add_f32_e32 v85, v111, v79
	v_add_f32_e32 v68, 1.0, v68
	v_rcp_f32_e32 v90, v68
	v_mul_f32_e32 v68, 0xbfb8aa3b, v89
	v_exp_f32_e32 v68, v68
	v_add_f32_e32 v80, v118, v86
	v_add_u32_e32 v86, 0x400, v194
	v_fmac_f32_e32 v123, v152, v122
	v_add_f32_e32 v82, v116, v105
	v_add_f32_e32 v83, v117, v104
	ds_write2_b32 v86, v84, v85 offset0:8 offset1:140
	v_add_u32_e32 v84, 0x2000, v194
	v_fmac_f32_e32 v147, v148, v123
	v_add_f32_e32 v81, v119, v87
	ds_write2_b32 v84, v82, v83 offset0:64 offset1:196
	v_add_u32_e32 v82, 0x2400, v194
	v_fmac_f32_e32 v146, v149, v147
	v_add_f32_e32 v78, v124, v92
	v_add_f32_e32 v79, v125, v93
	ds_write2_b32 v82, v80, v81 offset0:72 offset1:204
	v_add_u32_e32 v80, 0x4200, v194
	v_add_f32_e32 v68, 1.0, v68
	v_fmac_f32_e32 v145, v150, v146
	v_add_f32_e32 v76, v94, v122
	v_add_f32_e32 v77, v95, v123
	ds_write2_b32 v80, v78, v79 offset1:132
	v_add_u32_e32 v78, 0x4600, v194
	v_rcp_f32_e32 v91, v68
	v_fmac_f32_e32 v144, v151, v145
	v_add_f32_e32 v74, v100, v147
	v_add_f32_e32 v75, v101, v146
	ds_write2_b32 v78, v76, v77 offset0:8 offset1:140
	v_add_u32_e32 v76, 0x6200, v194
	v_add_f32_e32 v72, v102, v145
	v_add_f32_e32 v73, v103, v144
	ds_write2_b32 v76, v74, v75 offset0:64 offset1:196
	v_add_u32_e32 v74, 0x6600, v194
	ds_write2_b32 v74, v72, v73 offset0:72 offset1:204
	s_waitcnt lgkmcnt(0)
	s_barrier
	ds_read_b128 v[72:75], v186
	ds_read_b128 v[76:79], v186 offset:16
	ds_read_b128 v[80:83], v186 offset:32
	ds_read_b128 v[84:87], v186 offset:48
	v_mul_f32_e64 v88, v90, v88
	v_mul_f32_e64 v89, v91, v89
	s_waitcnt lgkmcnt(3)
	v_mul_f32_e64 v72, v88, v72
	v_mul_f32_e64 v73, v89, v73
	s_nop 0
	v_cvt_pk_bf16_f32 v68, v72, v73
	s_waitcnt vmcnt(0)
	v_lshlrev_b32_e32 v72, 16, v64
	v_and_b32_e32 v73, 0xffff0000, v64
	v_mul_f32_e32 v64, 0xbfb8aa3b, v72
	v_exp_f32_e32 v64, v64
	s_nop 0
	v_add_f32_e32 v64, 1.0, v64
	v_rcp_f32_e32 v88, v64
	v_mul_f32_e32 v64, 0xbfb8aa3b, v73
	v_exp_f32_e32 v64, v64
	s_nop 0
	v_add_f32_e32 v64, 1.0, v64
	v_rcp_f32_e32 v89, v64
	s_nop 0
	v_mul_f32_e64 v72, v88, v72
	v_mul_f32_e64 v73, v89, v73
	s_waitcnt lgkmcnt(1)
	v_mul_f32_e64 v72, v72, v80
	v_mul_f32_e64 v73, v73, v81
	s_nop 0
	v_cvt_pk_bf16_f32 v64, v72, v73
	v_lshlrev_b32_e32 v72, 16, v69
	v_and_b32_e32 v73, 0xffff0000, v69
	v_mul_f32_e32 v69, 0xbfb8aa3b, v72
	v_exp_f32_e32 v69, v69
	s_nop 0
	v_add_f32_e32 v69, 1.0, v69
	v_rcp_f32_e32 v80, v69
	v_mul_f32_e32 v69, 0xbfb8aa3b, v73
	v_exp_f32_e32 v69, v69
	s_nop 0
	v_add_f32_e32 v69, 1.0, v69
	v_rcp_f32_e32 v81, v69
	s_nop 0
	v_mul_f32_e64 v72, v80, v72
	v_mul_f32_e64 v73, v81, v73
	s_nop 0
	v_mul_f32_e64 v72, v72, v74
	v_mul_f32_e64 v73, v73, v75
	s_nop 0
	v_cvt_pk_bf16_f32 v69, v72, v73
	v_lshlrev_b32_e32 v72, 16, v65
	v_and_b32_e32 v73, 0xffff0000, v65
	v_mul_f32_e32 v65, 0xbfb8aa3b, v72
	v_exp_f32_e32 v65, v65
	s_nop 0
	v_add_f32_e32 v65, 1.0, v65
	v_rcp_f32_e32 v74, v65
	v_mul_f32_e32 v65, 0xbfb8aa3b, v73
	v_exp_f32_e32 v65, v65
	s_nop 0
	v_add_f32_e32 v65, 1.0, v65
	v_rcp_f32_e32 v75, v65
	s_nop 0
	v_mul_f32_e64 v72, v74, v72
	v_mul_f32_e64 v73, v75, v73
	s_nop 0
	v_mul_f32_e64 v72, v72, v82
	v_mul_f32_e64 v73, v73, v83
	s_nop 0
	v_cvt_pk_bf16_f32 v65, v72, v73
	v_lshlrev_b32_e32 v72, 16, v70
	v_and_b32_e32 v73, 0xffff0000, v70
	v_mul_f32_e32 v70, 0xbfb8aa3b, v72
	v_exp_f32_e32 v70, v70
	s_nop 0
	v_add_f32_e32 v70, 1.0, v70
	v_rcp_f32_e32 v74, v70
	v_mul_f32_e32 v70, 0xbfb8aa3b, v73
	v_exp_f32_e32 v70, v70
	s_nop 0
	v_add_f32_e32 v70, 1.0, v70
	v_rcp_f32_e32 v75, v70
	s_nop 0
	v_mul_f32_e64 v72, v74, v72
	v_mul_f32_e64 v73, v75, v73
	s_nop 0
	v_mul_f32_e64 v72, v72, v76
	v_mul_f32_e64 v73, v73, v77
	s_nop 0
	v_cvt_pk_bf16_f32 v70, v72, v73
	v_lshlrev_b32_e32 v72, 16, v66
	v_and_b32_e32 v73, 0xffff0000, v66
	v_mul_f32_e32 v66, 0xbfb8aa3b, v72
	v_exp_f32_e32 v66, v66
	s_nop 0
	v_add_f32_e32 v66, 1.0, v66
	v_rcp_f32_e32 v74, v66
	v_mul_f32_e32 v66, 0xbfb8aa3b, v73
	v_exp_f32_e32 v66, v66
	s_nop 0
	v_add_f32_e32 v66, 1.0, v66
	v_rcp_f32_e32 v75, v66
	s_nop 0
	v_mul_f32_e64 v72, v74, v72
	v_mul_f32_e64 v73, v75, v73
	s_waitcnt lgkmcnt(0)
	v_mul_f32_e64 v72, v72, v84
	v_mul_f32_e64 v73, v73, v85
	s_nop 0
	v_cvt_pk_bf16_f32 v66, v72, v73
	v_lshlrev_b32_e32 v72, 16, v71
	v_and_b32_e32 v73, 0xffff0000, v71
	v_mul_f32_e32 v71, 0xbfb8aa3b, v72
	v_exp_f32_e32 v71, v71
	s_nop 0
	v_add_f32_e32 v71, 1.0, v71
	v_rcp_f32_e32 v74, v71
	v_mul_f32_e32 v71, 0xbfb8aa3b, v73
	v_exp_f32_e32 v71, v71
	s_nop 0
	v_add_f32_e32 v71, 1.0, v71
	v_rcp_f32_e32 v75, v71
	s_nop 0
	v_mul_f32_e64 v72, v74, v72
	v_mul_f32_e64 v73, v75, v73
	s_nop 0
	v_mul_f32_e64 v72, v72, v78
	v_mul_f32_e64 v73, v73, v79
	s_nop 0
	v_cvt_pk_bf16_f32 v71, v72, v73
	v_lshlrev_b32_e32 v72, 16, v67
	v_and_b32_e32 v73, 0xffff0000, v67
	v_mul_f32_e32 v67, 0xbfb8aa3b, v72
	v_exp_f32_e32 v67, v67
	s_nop 0
	v_add_f32_e32 v67, 1.0, v67
	v_rcp_f32_e32 v74, v67
	v_mul_f32_e32 v67, 0xbfb8aa3b, v73
	v_exp_f32_e32 v67, v67
	s_nop 0
	v_add_f32_e32 v67, 1.0, v67
	v_rcp_f32_e32 v75, v67
	s_nop 0
	v_mul_f32_e64 v72, v74, v72
	v_mul_f32_e64 v73, v75, v73
	s_nop 0
	v_mul_f32_e64 v72, v72, v86
	v_mul_f32_e64 v73, v73, v87
	s_nop 0
	v_cvt_pk_bf16_f32 v67, v72, v73
	v_mad_i64_i32 v[72:73], s[16:17], v202, s90, v[180:181]
	global_store_dwordx4 v[72:73], v[68:71], off
	s_nop 1
	v_mad_i64_i32 v[68:69], s[16:17], v202, s90, v[182:183]
	v_add_co_u32_e32 v68, vcc, 0x17320000, v68
	s_nop 1
	v_addc_co_u32_e32 v69, vcc, 0, v69, vcc
	global_store_dwordx4 v[68:69], v[64:67], off offset:16
	s_cbranch_scc0 .LBB0_1674
	s_branch .LBB0_1657
